# batched loads: mod GEMV, transpose loop, oproj/fc2 epilogues, g1; early barrier invalidate
# speedup vs baseline: 1.0814x; 1.0683x over previous
.LBB0_69:
	ds_read_b128 v[60:63], v71 offset:32768
	ds_read_b128 v[76:79], v71 offset:34816
	ds_read_b128 v[80:83], v71 offset:36864
	ds_read_b128 v[84:87], v72 offset:49152
	ds_read_b128 v[88:91], v72 offset:51200
	ds_read_b128 v[92:95], v72 offset:53248
	ds_read_b128 v[96:99], v72 offset:55296
	s_waitcnt lgkmcnt(0)
	v_mfma_f32_16x16x32_bf16 v[44:47], v[84:87], v[60:63], v[44:47]
	v_mfma_f32_16x16x32_bf16 v[40:43], v[88:91], v[60:63], v[40:43]
	v_mfma_f32_16x16x32_bf16 v[36:39], v[92:95], v[60:63], v[36:39]
	v_mfma_f32_16x16x32_bf16 v[32:35], v[96:99], v[60:63], v[32:35]
	v_mfma_f32_16x16x32_bf16 v[28:31], v[84:87], v[76:79], v[28:31]
	v_mfma_f32_16x16x32_bf16 v[24:27], v[88:91], v[76:79], v[24:27]
	v_mfma_f32_16x16x32_bf16 v[20:23], v[92:95], v[76:79], v[20:23]
	v_mfma_f32_16x16x32_bf16 v[16:19], v[96:99], v[76:79], v[16:19]
	v_mfma_f32_16x16x32_bf16 v[12:15], v[84:87], v[80:83], v[12:15]
	v_mfma_f32_16x16x32_bf16 v[8:11], v[88:91], v[80:83], v[8:11]
	v_mfma_f32_16x16x32_bf16 v[4:7], v[92:95], v[80:83], v[4:7]
	v_mfma_f32_16x16x32_bf16 v[0:3], v[96:99], v[80:83], v[0:3]
	ds_read_b128 v[60:63], v73 offset:32768
	ds_read_b128 v[76:79], v73 offset:34816
	ds_read_b128 v[80:83], v73 offset:36864
	ds_read_b128 v[84:87], v74 offset:49152
	ds_read_b128 v[88:91], v74 offset:51200
	ds_read_b128 v[92:95], v74 offset:53248
	ds_read_b128 v[96:99], v74 offset:55296
	s_waitcnt lgkmcnt(0)
	v_mfma_f32_16x16x32_bf16 v[100:103], v[84:87], v[60:63], v[44:47]
	v_mfma_f32_16x16x32_bf16 v[40:43], v[88:91], v[60:63], v[40:43]
	v_mfma_f32_16x16x32_bf16 v[36:39], v[92:95], v[60:63], v[36:39]
	v_mfma_f32_16x16x32_bf16 v[32:35], v[96:99], v[60:63], v[32:35]
	v_mfma_f32_16x16x32_bf16 v[24:27], v[88:91], v[76:79], v[24:27]
	v_mfma_f32_16x16x32_bf16 v[8:11], v[88:91], v[80:83], v[8:11]
	v_mfma_f32_16x16x32_bf16 v[28:31], v[84:87], v[76:79], v[28:31]
	v_mfma_f32_16x16x32_bf16 v[20:23], v[92:95], v[76:79], v[20:23]
	v_mfma_f32_16x16x32_bf16 v[16:19], v[96:99], v[76:79], v[16:19]
	v_mfma_f32_16x16x32_bf16 v[4:7], v[92:95], v[80:83], v[4:7]
	v_mfma_f32_16x16x32_bf16 v[12:15], v[84:87], v[80:83], v[12:15]
	v_mfma_f32_16x16x32_bf16 v[0:3], v[96:99], v[80:83], v[0:3]
	v_add_u32_e32 v160, s8, v65
	v_or_b32_e32 v161, s10, v70
	v_lshlrev_b32_e32 v161, 2, v161
	v_lshl_add_u32 v162, v160, 12, v161
	v_add_u32_e32 v163, 0x10000, v162
	v_add_u32_e32 v164, 0x20000, v162
	v_readfirstlane_b32 s1, v160
	v_readlane_b32 s26, v248, 33
	v_readlane_b32 s27, v248, 34
	v_readlane_b32 s8, v247, 39
	v_readlane_b32 s9, v247, 40
	v_readlane_b32 s20, v249, 19
	v_readlane_b32 s21, v249, 20
	v_readlane_b32 s22, v249, 21
	v_readlane_b32 s23, v249, 22
	s_sub_u32 s22, s22, 0x1000000
	s_subb_u32 s23, s23, 0
	s_add_i32 s0, s1, 0xfffff000
	s_lshr_b32 s0, s0, 10
	s_add_i32 s0, s0, 1
	s_cmp_lt_u32 s1, 0x1000
	s_cselect_b32 s0, 0, s0
	s_add_i32 s0, s0, s17
	s_mul_i32 s0, s0, 0x6000
	s_add_u32 s14, s8, s0
	s_addc_u32 s15, s9, 0
	s_add_u32 s14, s14, 0x12000
	s_addc_u32 s15, s15, 0
	s_cmp_lt_u32 s1, 0x1000
	s_cselect_b32 s24, s20, s22
	s_cselect_b32 s25, s21, s23
	s_cmp_lg_u64 s[40:41], 0
	s_cselect_b32 s24, s24, s26
	s_cselect_b32 s25, s25, s27
	global_load_dwordx4 v[110:113], v162, s[24:25]
	global_load_dwordx4 v[114:117], v162, s[24:25] offset:64
	global_load_dwordx4 v[118:121], v162, s[24:25] offset:128
	global_load_dwordx4 v[122:125], v162, s[24:25] offset:192
	global_load_dwordx4 v[76:79], v161, s[14:15]
	global_load_dwordx4 v[80:83], v161, s[14:15] offset:64
	global_load_dwordx4 v[84:87], v161, s[14:15] offset:128
	global_load_dwordx4 v[88:91], v161, s[14:15] offset:192
	s_add_i32 s1, s1, 16
	s_add_i32 s0, s1, 0xfffff000
	s_lshr_b32 s0, s0, 10
	s_add_i32 s0, s0, 1
	s_cmp_lt_u32 s1, 0x1000
	s_cselect_b32 s0, 0, s0
	s_add_i32 s0, s0, s17
	s_mul_i32 s0, s0, 0x6000
	s_add_u32 s14, s8, s0
	s_addc_u32 s15, s9, 0
	s_add_u32 s14, s14, 0x12000
	s_addc_u32 s15, s15, 0
	s_cmp_lt_u32 s1, 0x1000
	s_cselect_b32 s24, s20, s22
	s_cselect_b32 s25, s21, s23
	s_cmp_lg_u64 s[40:41], 0
	s_cselect_b32 s24, s24, s26
	s_cselect_b32 s25, s25, s27
	global_load_dwordx4 v[126:129], v163, s[24:25]
	global_load_dwordx4 v[130:133], v163, s[24:25] offset:64
	global_load_dwordx4 v[134:137], v163, s[24:25] offset:128
	global_load_dwordx4 v[138:141], v163, s[24:25] offset:192
	global_load_dwordx4 v[92:95], v161, s[14:15]
	global_load_dwordx4 v[96:99], v161, s[14:15] offset:64
	global_load_dwordx4 v[220:223], v161, s[14:15] offset:128
	global_load_dwordx4 v[174:177], v161, s[14:15] offset:192
	s_add_i32 s1, s1, 16
	s_add_i32 s0, s1, 0xfffff000
	s_lshr_b32 s0, s0, 10
	s_add_i32 s0, s0, 1
	s_cmp_lt_u32 s1, 0x1000
	s_cselect_b32 s0, 0, s0
	s_add_i32 s0, s0, s17
	s_mul_i32 s0, s0, 0x6000
	s_add_u32 s14, s8, s0
	s_addc_u32 s15, s9, 0
	s_add_u32 s14, s14, 0x12000
	s_addc_u32 s15, s15, 0
	s_cmp_lt_u32 s1, 0x1000
	s_cselect_b32 s24, s20, s22
	s_cselect_b32 s25, s21, s23
	s_cmp_lg_u64 s[40:41], 0
	s_cselect_b32 s24, s24, s26
	s_cselect_b32 s25, s25, s27
	global_load_dwordx4 v[142:145], v164, s[24:25]
	global_load_dwordx4 v[146:149], v164, s[24:25] offset:64
	global_load_dwordx4 v[212:215], v164, s[24:25] offset:128
	global_load_dwordx4 v[216:219], v164, s[24:25] offset:192
	global_load_dwordx4 v[178:181], v161, s[14:15]
	global_load_dwordx4 v[234:237], v161, s[14:15] offset:64
	global_load_dwordx4 v[238:241], v161, s[14:15] offset:128
	global_load_dwordx4 v[242:245], v161, s[14:15] offset:192
	s_waitcnt vmcnt(16)
	v_pk_fma_f32 v[110:111], v[100:101], v[76:77], v[110:111]
	v_pk_fma_f32 v[112:113], v[102:103], v[78:79], v[112:113]
	v_pk_fma_f32 v[114:115], v[40:41], v[80:81], v[114:115]
	v_pk_fma_f32 v[116:117], v[42:43], v[82:83], v[116:117]
	v_pk_fma_f32 v[118:119], v[36:37], v[84:85], v[118:119]
	v_pk_fma_f32 v[120:121], v[38:39], v[86:87], v[120:121]
	v_pk_fma_f32 v[122:123], v[32:33], v[88:89], v[122:123]
	v_pk_fma_f32 v[124:125], v[34:35], v[90:91], v[124:125]
	global_store_dwordx4 v162, v[110:113], s[26:27] nt
	global_store_dwordx4 v162, v[114:117], s[26:27] offset:64 nt
	global_store_dwordx4 v162, v[118:121], s[26:27] offset:128 nt
	global_store_dwordx4 v162, v[122:125], s[26:27] offset:192 nt
	s_waitcnt vmcnt(12)
	v_pk_fma_f32 v[126:127], v[28:29], v[92:93], v[126:127]
	v_pk_fma_f32 v[128:129], v[30:31], v[94:95], v[128:129]
	v_pk_fma_f32 v[130:131], v[24:25], v[96:97], v[130:131]
	v_pk_fma_f32 v[132:133], v[26:27], v[98:99], v[132:133]
	v_pk_fma_f32 v[134:135], v[20:21], v[220:221], v[134:135]
	v_pk_fma_f32 v[136:137], v[22:23], v[222:223], v[136:137]
	v_pk_fma_f32 v[138:139], v[16:17], v[174:175], v[138:139]
	v_pk_fma_f32 v[140:141], v[18:19], v[176:177], v[140:141]
	global_store_dwordx4 v163, v[126:129], s[26:27] nt
	global_store_dwordx4 v163, v[130:133], s[26:27] offset:64 nt
	global_store_dwordx4 v163, v[134:137], s[26:27] offset:128 nt
	global_store_dwordx4 v163, v[138:141], s[26:27] offset:192 nt
	s_waitcnt vmcnt(8)
	v_pk_fma_f32 v[142:143], v[12:13], v[178:179], v[142:143]
	v_pk_fma_f32 v[144:145], v[14:15], v[180:181], v[144:145]
	v_pk_fma_f32 v[146:147], v[8:9], v[234:235], v[146:147]
	v_pk_fma_f32 v[148:149], v[10:11], v[236:237], v[148:149]
	v_pk_fma_f32 v[212:213], v[4:5], v[238:239], v[212:213]
	v_pk_fma_f32 v[214:215], v[6:7], v[240:241], v[214:215]
	v_pk_fma_f32 v[216:217], v[0:1], v[242:243], v[216:217]
	v_pk_fma_f32 v[218:219], v[2:3], v[244:245], v[218:219]
	global_store_dwordx4 v164, v[142:145], s[26:27] nt
	global_store_dwordx4 v164, v[146:149], s[26:27] offset:64 nt
	global_store_dwordx4 v164, v[212:215], s[26:27] offset:128 nt
	global_store_dwordx4 v164, v[216:219], s[26:27] offset:192 nt
	s_mov_b64 s[0:1], 0x20000
	s_movk_i32 s10, 0x1800
	s_mov_b64 s[14:15], 0x12000
	v_readlane_b32 s20, v248, 27
	v_readlane_b32 s21, v248, 28
	v_readlane_b32 s22, v248, 29
	v_readlane_b32 s23, v248, 30
	v_readlane_b32 s24, v248, 31
	v_readlane_b32 s25, v248, 32
	v_readlane_b32 s26, v248, 33
	v_readlane_b32 s27, v248, 34
	s_cmp_eq_u32 s18, s16
	s_mov_b64 s[8:9], s[2:3]
	s_cbranch_scc1 .LBB0_90

.LBB0_184:
	s_andn2_saveexec_b64 s[0:1], s[8:9]
	v_ashrrev_i32_e32 v10, 6, v0
	v_bfe_u32 v13, v0, 3, 3
	v_and_b32_e32 v16, 7, v0
	v_mov_b32_e32 v12, 3
	s_or_b64 s[2:3], s[2:3], exec
	s_or_b64 exec, exec, s[0:1]
	s_xor_b64 s[0:1], s[2:3], -1
	s_and_saveexec_b64 s[2:3], s[0:1]
	s_xor_b64 s[44:45], exec, s[2:3]
	s_cbranch_execz .LBB0_196
	v_mov_b32_e32 v33, v167
	s_movk_i32 s0, 0x80
	v_lshlrev_b32_e32 v32, 5, v12
	v_cmp_gt_i32_e32 vcc, s0, v33
	v_lshlrev_b32_e32 v11, 2, v33
	s_barrier
	s_and_saveexec_b64 s[0:1], vcc
	s_cbranch_execz .LBB0_189
	v_ashrrev_i32_e32 v4, 2, v33
	v_sub_u32_e32 v0, 31, v4
	v_cmp_eq_u32_e32 vcc, 0, v13
	s_movk_i32 s2, 0x3700
	v_lshlrev_b32_e32 v152, 5, v13
	v_cndmask_b32_e32 v0, v0, v4, vcc
	v_add_u32_e32 v2, v0, v32
	v_mov_b64_e32 v[0:1], s[60:61]
	v_mad_i64_i32 v[0:1], s[2:3], v2, s2, v[0:1]
	v_and_b32_e32 v5, 12, v11
	v_lshl_add_u64 v[0:1], v[0:1], 0, v[152:153]
	v_lshlrev_b32_e32 v152, 1, v5
	v_lshl_add_u64 v[0:1], v[0:1], 0, v[152:153]
	global_load_dwordx2 v[242:243], v[0:1], off offset:3072
	v_lshlrev_b32_e32 v5, 2, v5
	v_lshl_or_b32 v244, v4, 6, v5
.LBB0_189:
	s_or_b64 exec, exec, s[0:1]
	v_ashrrev_i32_e32 v55, 6, v33
	v_lshlrev_b32_e32 v28, 3, v55
	v_cmp_eq_u32_e64 s[40:41], 0, v13
	v_sub_u32_e32 v0, 31, v28
	v_lshlrev_b32_e32 v8, 6, v10
	v_cndmask_b32_e64 v29, v0, v28, s[40:41]
	v_ashrrev_i32_e32 v9, 31, v8
	v_add_u32_e32 v0, v29, v32
	v_mov_b64_e32 v[4:5], s[60:61]
	s_movk_i32 s2, 0x3700
	v_and_b32_e32 v54, 63, v33
	v_mad_i64_i32 v[0:1], s[0:1], v0, s2, v[4:5]
	v_lshlrev_b64 v[2:3], 1, v[8:9]
	v_lshl_add_u64 v[0:1], v[0:1], 0, v[2:3]
	v_lshlrev_b32_e32 v152, 1, v54
	v_lshl_add_u64 v[0:1], v[0:1], 0, v[152:153]
	v_or_b32_e32 v27, 1, v28
	global_load_ushort v30, v[0:1], off
	global_load_ushort v31, v[0:1], off offset:512
	v_sub_u32_e32 v0, 31, v27
	v_cndmask_b32_e64 v26, v0, v27, s[40:41]
	v_add_u32_e32 v0, v26, v32
	v_mad_i64_i32 v[0:1], s[0:1], v0, s2, v[4:5]
	v_lshl_add_u64 v[0:1], v[0:1], 0, v[2:3]
	v_lshl_add_u64 v[0:1], v[0:1], 0, v[152:153]
	v_or_b32_e32 v25, 2, v28
	global_load_ushort v34, v[0:1], off
	global_load_ushort v35, v[0:1], off offset:512
	v_sub_u32_e32 v0, 31, v25
	v_cndmask_b32_e64 v24, v0, v25, s[40:41]
	v_add_u32_e32 v0, v24, v32
	v_mad_i64_i32 v[0:1], s[0:1], v0, s2, v[4:5]
	v_lshl_add_u64 v[0:1], v[0:1], 0, v[2:3]
	v_lshl_add_u64 v[0:1], v[0:1], 0, v[152:153]
	v_or_b32_e32 v23, 3, v28
	global_load_ushort v36, v[0:1], off
	global_load_ushort v37, v[0:1], off offset:512
	v_sub_u32_e32 v0, 31, v23
	v_cndmask_b32_e64 v22, v0, v23, s[40:41]
	v_add_u32_e32 v0, v22, v32
	v_mad_i64_i32 v[0:1], s[0:1], v0, s2, v[4:5]
	v_lshl_add_u64 v[0:1], v[0:1], 0, v[2:3]
	v_lshl_add_u64 v[0:1], v[0:1], 0, v[152:153]
	v_or_b32_e32 v21, 4, v28
	global_load_ushort v38, v[0:1], off
	global_load_ushort v39, v[0:1], off offset:512
	v_sub_u32_e32 v0, 31, v21
	v_cndmask_b32_e64 v20, v0, v21, s[40:41]
	v_add_u32_e32 v0, v20, v32
	v_mad_i64_i32 v[0:1], s[0:1], v0, s2, v[4:5]
	v_lshl_add_u64 v[0:1], v[0:1], 0, v[2:3]
	v_lshl_add_u64 v[0:1], v[0:1], 0, v[152:153]
	v_or_b32_e32 v19, 5, v28
	global_load_ushort v40, v[0:1], off
	global_load_ushort v41, v[0:1], off offset:512
	v_sub_u32_e32 v0, 31, v19
	v_cndmask_b32_e64 v18, v0, v19, s[40:41]
	v_add_u32_e32 v0, v18, v32
	v_mad_i64_i32 v[0:1], s[0:1], v0, s2, v[4:5]
	v_lshl_add_u64 v[0:1], v[0:1], 0, v[2:3]
	v_lshl_add_u64 v[0:1], v[0:1], 0, v[152:153]
	v_or_b32_e32 v17, 6, v28
	global_load_ushort v42, v[0:1], off
	global_load_ushort v43, v[0:1], off offset:512
	v_sub_u32_e32 v0, 31, v17
	v_cndmask_b32_e64 v16, v0, v17, s[40:41]
	v_add_u32_e32 v0, v16, v32
	v_mad_i64_i32 v[0:1], s[0:1], v0, s2, v[4:5]
	v_lshl_add_u64 v[0:1], v[0:1], 0, v[2:3]
	v_lshl_add_u64 v[0:1], v[0:1], 0, v[152:153]
	v_or_b32_e32 v15, 7, v28
	global_load_ushort v44, v[0:1], off
	global_load_ushort v45, v[0:1], off offset:512
	v_sub_u32_e32 v0, 31, v15
	v_cndmask_b32_e64 v14, v0, v15, s[40:41]
	v_add_u32_e32 v0, v14, v32
	v_mad_i64_i32 v[0:1], s[0:1], v0, s2, v[4:5]
	v_lshl_add_u64 v[0:1], v[0:1], 0, v[2:3]
	v_lshl_add_u64 v[0:1], v[0:1], 0, v[152:153]
	global_load_ushort v46, v[0:1], off
	global_load_ushort v47, v[0:1], off offset:512
	v_add_u32_e32 v0, 0x100, v33
	v_ashrrev_i32_e32 v51, 4, v33
	v_ashrrev_i32_e32 v50, 4, v0
	v_sub_u32_e32 v0, 31, v51
	v_sub_u32_e32 v53, 31, v50
	v_cndmask_b32_e64 v0, v0, v51, s[40:41]
	v_lshlrev_b32_e32 v48, 7, v10
	v_cndmask_b32_e64 v53, v53, v50, s[40:41]
	v_add_u32_e32 v0, v0, v32
	v_ashrrev_i32_e32 v49, 31, v48
	v_lshlrev_b32_e32 v56, 3, v33
	v_add_u32_e32 v53, v53, v32
	v_mad_i64_i32 v[0:1], s[0:1], v0, s2, v[4:5]
	v_lshlrev_b64 v[6:7], 1, v[48:49]
	v_and_b32_e32 v52, 0x78, v56
	v_mad_i64_i32 v[4:5], s[0:1], v53, s2, v[4:5]
	v_lshl_add_u64 v[0:1], v[0:1], 0, v[6:7]
	v_lshlrev_b32_e32 v152, 1, v52
	v_lshl_add_u64 v[4:5], v[4:5], 0, v[6:7]
	v_readlane_b32 s2, v249, 1
	v_lshl_add_u64 v[0:1], v[0:1], 0, v[152:153]
	v_lshl_add_u64 v[4:5], v[4:5], 0, v[152:153]
	v_cndmask_b32_e64 v152, v187, v188, s[40:41]
	v_readlane_b32 s3, v249, 2
	v_readlane_b32 s0, v247, 51
	v_readlane_b32 s1, v247, 52
	s_cmp_lg_u64 s[40:41], 0
	s_movk_i32 s101, 0x80
	s_cselect_b32 s100, 0x70, s101
	s_load_dwordx2 s[100:101], s[2:3], s100
	v_lshlrev_b32_e32 v152, 2, v54
	global_load_dwordx4 v[0:3], v[0:1], off offset:1024
	s_mov_b32 s8, 0x7f800000
	global_load_dwordx4 v[4:7], v[4:5], off offset:1024
	v_mul_u32_u24_e32 v52, 40, v52
	v_lshlrev_b32_e32 v52, 1, v52
	v_lshl_add_u32 v51, v51, 1, v52
	s_waitcnt lgkmcnt(0)
	v_mov_b32_e32 v58, s100
	v_mov_b32_e32 v59, s101
	v_lshl_add_u64 v[58:59], v[58:59], 0, s[0:1]
	v_lshl_add_u64 v[58:59], v[8:9], 2, v[58:59]
	v_lshl_add_u64 v[72:73], v[58:59], 0, v[152:153]
	s_movk_i32 s0, 0x1000
	v_add_co_u32_e32 v58, vcc, s0, v72
	s_movk_i32 s0, 0x2000
	s_nop 0
	v_addc_co_u32_e32 v59, vcc, 0, v73, vcc
	v_add_co_u32_e32 v74, vcc, s0, v72
	s_movk_i32 s0, 0x3000
	s_nop 0
	v_addc_co_u32_e32 v75, vcc, 0, v73, vcc
	global_load_dword v67, v[72:73], off
	global_load_dword v70, v[72:73], off offset:1024
	global_load_dword v68, v[72:73], off offset:2048
	global_load_dword v69, v[72:73], off offset:3072
	v_add_co_u32_e32 v72, vcc, s0, v72
	global_load_dword v63, v[74:75], off offset:-4096
	global_load_dword v66, v[58:59], off offset:1024
	global_load_dword v64, v[58:59], off offset:2048
	global_load_dword v65, v[58:59], off offset:3072
	s_nop 0
	global_load_dword v59, v[74:75], off
	global_load_dword v62, v[74:75], off offset:1024
	global_load_dword v60, v[74:75], off offset:2048
	global_load_dword v61, v[74:75], off offset:3072
	v_addc_co_u32_e32 v73, vcc, 0, v73, vcc
	global_load_dword v53, v[72:73], off
	global_load_dword v58, v[72:73], off offset:1024
	global_load_dword v57, v[72:73], off offset:2048
	global_load_dword v9, v[72:73], off offset:3072
	s_cmp_lg_u64 s[40:41], 0
	s_movk_i32 s101, 0x88
	s_cselect_b32 s100, 0x78, s101
	s_load_dwordx2 s[100:101], s[2:3], s100
	v_readlane_b32 s0, v247, 53
	s_mov_b32 s2, 0xbfb8aa3b
	s_mov_b32 s1, 0x800000
	v_add_u32_e32 v8, s0, v8
	v_or_b32_e32 v74, v54, v8
	v_ashrrev_i32_e32 v75, 31, v74
	v_lshlrev_b32_e32 v8, 9, v55
	s_mov_b32 s3, 0x3f317217
	s_mov_b32 s0, 0x3d800000
	s_waitcnt lgkmcnt(0)
	v_mov_b32_e32 v72, s100
	v_mov_b32_e32 v73, s101
	v_lshl_add_u64 v[72:73], v[74:75], 2, v[72:73]
	global_load_dword v72, v[72:73], off
	v_cmp_gt_u32_e32 vcc, 0x80, v167
	s_waitcnt vmcnt(0)
	s_and_saveexec_b64 s[100:101], vcc
	v_lshlrev_b32_e32 v236, 16, v242
	v_and_b32_e32 v237, 0xffff0000, v242
	v_lshlrev_b32_e32 v238, 16, v243
	v_and_b32_e32 v239, 0xffff0000, v243
	ds_write_b128 v244, v[236:239] offset:23552
	s_or_b64 exec, exec, s[100:101]
	s_waitcnt lgkmcnt(0)
	s_barrier
	ds_read_b128 v[74:77], v8 offset:23552
	ds_read_b128 v[78:81], v8 offset:23568
	ds_read_b128 v[82:85], v8 offset:23584
	ds_read_b128 v[86:89], v8 offset:23600
	s_waitcnt lgkmcnt(3)
	v_mul_f32_e32 v71, v70, v75
	v_fmac_f32_e32 v71, v67, v74
	s_waitcnt lgkmcnt(2)
	v_mul_f32_e32 v73, v66, v79
	v_fmac_f32_e32 v71, v68, v76
	v_fmac_f32_e32 v73, v63, v78
	v_fmac_f32_e32 v71, v69, v77
	v_fmac_f32_e32 v73, v64, v80
	v_fmac_f32_e32 v73, v65, v81
	s_waitcnt vmcnt(0)
	v_add_f32_e32 v71, v72, v71
	v_add_f32_e32 v71, v71, v73
	s_waitcnt lgkmcnt(1)
	v_mul_f32_e32 v73, v62, v83
	v_fmac_f32_e32 v73, v59, v82
	v_fmac_f32_e32 v73, v60, v84
	v_fmac_f32_e32 v73, v61, v85
	v_add_f32_e32 v71, v71, v73
	s_waitcnt lgkmcnt(0)
	v_mul_f32_e32 v73, v58, v87
	v_fmac_f32_e32 v73, v53, v86
	v_fmac_f32_e32 v73, v57, v88
	v_fmac_f32_e32 v73, v9, v89
	v_add_f32_e32 v71, v71, v73
	v_min_f32_e32 v73, 0, v71
	v_mul_f32_e64 v71, |v71|, s2
	v_exp_f32_e32 v71, v71
	s_nop 0
	v_add_f32_e32 v71, 1.0, v71
	v_cmp_gt_f32_e32 vcc, s1, v71
	s_nop 1
	v_cndmask_b32_e64 v74, 0, 32, vcc
	v_ldexp_f32 v71, v71, v74
	v_log_f32_e32 v71, v71
	s_nop 0
	v_mul_f32_e32 v74, 0x3f317217, v71
	v_fma_f32 v74, v71, s3, -v74
	v_fmac_f32_e32 v74, 0x3377d1cf, v71
	v_fmac_f32_e32 v74, 0x3f317217, v71
	v_cmp_lt_f32_e64 s[42:43], |v71|, s8
	s_nop 1
	v_cndmask_b32_e64 v71, v71, v74, s[42:43]
	v_cndmask_b32_e32 v74, 0, v191, vcc
	v_sub_f32_e32 v71, v71, v74
	ds_read_b128 v[74:77], v8 offset:23616
	v_sub_f32_e32 v71, v73, v71
	v_fma_f32 v71, v71, s0, 0
	s_waitcnt lgkmcnt(0)
	v_mul_f32_e32 v73, v70, v75
	v_fmac_f32_e32 v73, v67, v74
	v_fmac_f32_e32 v73, v68, v76
	v_fmac_f32_e32 v73, v69, v77
	ds_read_b128 v[74:77], v8 offset:23632
	v_add_f32_e32 v73, v72, v73
	s_waitcnt lgkmcnt(0)
	v_mul_f32_e32 v75, v66, v75
	v_fmac_f32_e32 v75, v63, v74
	v_fmac_f32_e32 v75, v64, v76
	v_fmac_f32_e32 v75, v65, v77
	v_add_f32_e32 v73, v73, v75
	ds_read_b128 v[74:77], v8 offset:23648
	s_waitcnt lgkmcnt(0)
	v_mul_f32_e32 v75, v62, v75
	v_fmac_f32_e32 v75, v59, v74
	v_fmac_f32_e32 v75, v60, v76
	v_fmac_f32_e32 v75, v61, v77
	v_add_f32_e32 v73, v73, v75
	ds_read_b128 v[74:77], v8 offset:23664
	s_waitcnt lgkmcnt(0)
	v_mul_f32_e32 v75, v58, v75
	v_fmac_f32_e32 v75, v53, v74
	v_fmac_f32_e32 v75, v57, v76
	v_fmac_f32_e32 v75, v9, v77
	v_add_f32_e32 v73, v73, v75
	v_min_f32_e32 v74, 0, v73
	v_mul_f32_e64 v73, |v73|, s2
	v_exp_f32_e32 v73, v73
	s_nop 0
	v_add_f32_e32 v73, 1.0, v73
	v_cmp_gt_f32_e32 vcc, s1, v73
	s_nop 1
	v_cndmask_b32_e64 v75, 0, 32, vcc
	v_ldexp_f32 v73, v73, v75
	v_log_f32_e32 v73, v73
	s_nop 0
	v_mul_f32_e32 v75, 0x3f317217, v73
	v_fma_f32 v75, v73, s3, -v75
	v_fmac_f32_e32 v75, 0x3377d1cf, v73
	v_fmac_f32_e32 v75, 0x3f317217, v73
	v_cmp_lt_f32_e64 s[42:43], |v73|, s8
	s_nop 1
	v_cndmask_b32_e64 v73, v73, v75, s[42:43]
	v_cndmask_b32_e32 v75, 0, v191, vcc
	v_sub_f32_e32 v73, v73, v75
	v_sub_f32_e32 v73, v74, v73
	ds_read_b128 v[74:77], v8 offset:23680
	v_fmamk_f32 v73, v73, 0x3d800000, v71
	s_waitcnt lgkmcnt(0)
	v_mul_f32_e32 v75, v70, v75
	v_fmac_f32_e32 v75, v67, v74
	v_fmac_f32_e32 v75, v68, v76
	v_fmac_f32_e32 v75, v69, v77
	v_add_f32_e32 v78, v72, v75
	ds_read_b128 v[74:77], v8 offset:23696
	s_waitcnt lgkmcnt(0)
	v_mul_f32_e32 v75, v66, v75
	v_fmac_f32_e32 v75, v63, v74
	v_fmac_f32_e32 v75, v64, v76
	v_fmac_f32_e32 v75, v65, v77
	v_add_f32_e32 v78, v78, v75
	ds_read_b128 v[74:77], v8 offset:23712
	s_waitcnt lgkmcnt(0)
	v_mul_f32_e32 v75, v62, v75
	v_fmac_f32_e32 v75, v59, v74
	v_fmac_f32_e32 v75, v60, v76
	v_fmac_f32_e32 v75, v61, v77
	v_add_f32_e32 v78, v78, v75
	ds_read_b128 v[74:77], v8 offset:23728
	s_waitcnt lgkmcnt(0)
	v_mul_f32_e32 v75, v58, v75
	v_fmac_f32_e32 v75, v53, v74
	v_fmac_f32_e32 v75, v57, v76
	v_fmac_f32_e32 v75, v9, v77
	v_add_f32_e32 v74, v78, v75
	v_min_f32_e32 v75, 0, v74
	v_mul_f32_e64 v74, |v74|, s2
	v_exp_f32_e32 v74, v74
	s_nop 0
	v_add_f32_e32 v74, 1.0, v74
	v_cmp_gt_f32_e32 vcc, s1, v74
	s_nop 1
	v_cndmask_b32_e64 v76, 0, 32, vcc
	v_ldexp_f32 v74, v74, v76
	v_log_f32_e32 v74, v74
	s_nop 0
	v_mul_f32_e32 v76, 0x3f317217, v74
	v_fma_f32 v76, v74, s3, -v76
	v_fmac_f32_e32 v76, 0x3377d1cf, v74
	v_fmac_f32_e32 v76, 0x3f317217, v74
	v_cmp_lt_f32_e64 s[42:43], |v74|, s8
	s_nop 1
	v_cndmask_b32_e64 v74, v74, v76, s[42:43]
	v_cndmask_b32_e32 v76, 0, v191, vcc
	v_sub_f32_e32 v74, v74, v76
	ds_read_b128 v[76:79], v8 offset:23744
	v_sub_f32_e32 v74, v75, v74
	v_fmamk_f32 v74, v74, 0x3d800000, v73
	s_waitcnt lgkmcnt(0)
	v_mul_f32_e32 v75, v70, v77
	v_fmac_f32_e32 v75, v67, v76
	v_fmac_f32_e32 v75, v68, v78
	v_fmac_f32_e32 v75, v69, v79
	ds_read_b128 v[76:79], v8 offset:23760
	v_add_f32_e32 v75, v72, v75
	s_waitcnt lgkmcnt(0)
	v_mul_f32_e32 v77, v66, v77
	v_fmac_f32_e32 v77, v63, v76
	v_fmac_f32_e32 v77, v64, v78
	v_fmac_f32_e32 v77, v65, v79
	v_add_f32_e32 v75, v75, v77
	ds_read_b128 v[76:79], v8 offset:23776
	s_waitcnt lgkmcnt(0)
	v_mul_f32_e32 v77, v62, v77
	v_fmac_f32_e32 v77, v59, v76
	v_fmac_f32_e32 v77, v60, v78
	v_fmac_f32_e32 v77, v61, v79
	v_add_f32_e32 v75, v75, v77
	ds_read_b128 v[76:79], v8 offset:23792
	s_waitcnt lgkmcnt(0)
	v_mul_f32_e32 v77, v58, v77
	v_fmac_f32_e32 v77, v53, v76
	v_fmac_f32_e32 v77, v57, v78
	v_fmac_f32_e32 v77, v9, v79
	v_add_f32_e32 v75, v75, v77
	v_min_f32_e32 v76, 0, v75
	v_mul_f32_e64 v75, |v75|, s2
	v_exp_f32_e32 v75, v75
	s_nop 0
	v_add_f32_e32 v75, 1.0, v75
	v_cmp_gt_f32_e32 vcc, s1, v75
	s_nop 1
	v_cndmask_b32_e64 v77, 0, 32, vcc
	v_ldexp_f32 v75, v75, v77
	v_log_f32_e32 v75, v75
	s_nop 0
	v_mul_f32_e32 v77, 0x3f317217, v75
	v_fma_f32 v77, v75, s3, -v77
	v_fmac_f32_e32 v77, 0x3377d1cf, v75
	v_fmac_f32_e32 v77, 0x3f317217, v75
	v_cmp_lt_f32_e64 s[42:43], |v75|, s8
	s_nop 1
	v_cndmask_b32_e64 v75, v75, v77, s[42:43]
	v_cndmask_b32_e32 v77, 0, v191, vcc
	v_sub_f32_e32 v75, v75, v77
	v_sub_f32_e32 v75, v76, v75
	ds_read_b128 v[76:79], v8 offset:23808
	v_fmamk_f32 v75, v75, 0x3d800000, v74
	s_waitcnt lgkmcnt(0)
	v_mul_f32_e32 v77, v70, v77
	v_fmac_f32_e32 v77, v67, v76
	v_fmac_f32_e32 v77, v68, v78
	v_fmac_f32_e32 v77, v69, v79
	v_add_f32_e32 v80, v72, v77
	ds_read_b128 v[76:79], v8 offset:23824
	s_waitcnt lgkmcnt(0)
	v_mul_f32_e32 v77, v66, v77
	v_fmac_f32_e32 v77, v63, v76
	v_fmac_f32_e32 v77, v64, v78
	v_fmac_f32_e32 v77, v65, v79
	v_add_f32_e32 v80, v80, v77
	ds_read_b128 v[76:79], v8 offset:23840
	s_waitcnt lgkmcnt(0)
	v_mul_f32_e32 v77, v62, v77
	v_fmac_f32_e32 v77, v59, v76
	v_fmac_f32_e32 v77, v60, v78
	v_fmac_f32_e32 v77, v61, v79
	v_add_f32_e32 v80, v80, v77
	ds_read_b128 v[76:79], v8 offset:23856
	s_waitcnt lgkmcnt(0)
	v_mul_f32_e32 v77, v58, v77
	v_fmac_f32_e32 v77, v53, v76
	v_fmac_f32_e32 v77, v57, v78
	v_fmac_f32_e32 v77, v9, v79
	v_add_f32_e32 v76, v80, v77
	v_min_f32_e32 v77, 0, v76
	v_mul_f32_e64 v76, |v76|, s2
	v_exp_f32_e32 v76, v76
	s_nop 0
	v_add_f32_e32 v76, 1.0, v76
	v_cmp_gt_f32_e32 vcc, s1, v76
	s_nop 1
	v_cndmask_b32_e64 v78, 0, 32, vcc
	v_ldexp_f32 v76, v76, v78
	v_log_f32_e32 v76, v76
	s_nop 0
	v_mul_f32_e32 v78, 0x3f317217, v76
	v_fma_f32 v78, v76, s3, -v78
	v_fmac_f32_e32 v78, 0x3377d1cf, v76
	v_fmac_f32_e32 v78, 0x3f317217, v76
	v_cmp_lt_f32_e64 s[42:43], |v76|, s8
	s_nop 1
	v_cndmask_b32_e64 v76, v76, v78, s[42:43]
	v_cndmask_b32_e32 v78, 0, v191, vcc
	v_sub_f32_e32 v76, v76, v78
	ds_read_b128 v[78:81], v8 offset:23872
	v_sub_f32_e32 v76, v77, v76
	v_fmamk_f32 v76, v76, 0x3d800000, v75
	s_waitcnt lgkmcnt(0)
	v_mul_f32_e32 v77, v70, v79
	v_fmac_f32_e32 v77, v67, v78
	v_fmac_f32_e32 v77, v68, v80
	v_fmac_f32_e32 v77, v69, v81
	ds_read_b128 v[78:81], v8 offset:23888
	v_add_f32_e32 v77, v72, v77
	s_waitcnt lgkmcnt(0)
	v_mul_f32_e32 v79, v66, v79
	v_fmac_f32_e32 v79, v63, v78
	v_fmac_f32_e32 v79, v64, v80
	v_fmac_f32_e32 v79, v65, v81
	v_add_f32_e32 v77, v77, v79
	ds_read_b128 v[78:81], v8 offset:23904
	s_waitcnt lgkmcnt(0)
	v_mul_f32_e32 v79, v62, v79
	v_fmac_f32_e32 v79, v59, v78
	v_fmac_f32_e32 v79, v60, v80
	v_fmac_f32_e32 v79, v61, v81
	v_add_f32_e32 v77, v77, v79
	ds_read_b128 v[78:81], v8 offset:23920
	s_waitcnt lgkmcnt(0)
	v_mul_f32_e32 v79, v58, v79
	v_fmac_f32_e32 v79, v53, v78
	v_fmac_f32_e32 v79, v57, v80
	v_fmac_f32_e32 v79, v9, v81
	v_add_f32_e32 v77, v77, v79
	v_min_f32_e32 v78, 0, v77
	v_mul_f32_e64 v77, |v77|, s2
	v_exp_f32_e32 v77, v77
	s_nop 0
	v_add_f32_e32 v77, 1.0, v77
	v_cmp_gt_f32_e32 vcc, s1, v77
	s_nop 1
	v_cndmask_b32_e64 v79, 0, 32, vcc
	v_ldexp_f32 v77, v77, v79
	v_log_f32_e32 v77, v77
	s_nop 0
	v_mul_f32_e32 v79, 0x3f317217, v77
	v_fma_f32 v79, v77, s3, -v79
	v_fmac_f32_e32 v79, 0x3377d1cf, v77
	v_fmac_f32_e32 v79, 0x3f317217, v77
	v_cmp_lt_f32_e64 s[42:43], |v77|, s8
	s_nop 1
	v_cndmask_b32_e64 v77, v77, v79, s[42:43]
	v_cndmask_b32_e32 v79, 0, v191, vcc
	v_sub_f32_e32 v77, v77, v79
	v_sub_f32_e32 v77, v78, v77
	ds_read_b128 v[78:81], v8 offset:23936
	v_fmamk_f32 v77, v77, 0x3d800000, v76
	s_waitcnt lgkmcnt(0)
	v_mul_f32_e32 v79, v70, v79
	v_fmac_f32_e32 v79, v67, v78
	v_fmac_f32_e32 v79, v68, v80
	v_fmac_f32_e32 v79, v69, v81
	v_add_f32_e32 v82, v72, v79
	ds_read_b128 v[78:81], v8 offset:23952
	s_waitcnt lgkmcnt(0)
	v_mul_f32_e32 v79, v66, v79
	v_fmac_f32_e32 v79, v63, v78
	v_fmac_f32_e32 v79, v64, v80
	v_fmac_f32_e32 v79, v65, v81
	v_add_f32_e32 v82, v82, v79
	ds_read_b128 v[78:81], v8 offset:23968
	s_waitcnt lgkmcnt(0)
	v_mul_f32_e32 v79, v62, v79
	v_fmac_f32_e32 v79, v59, v78
	v_fmac_f32_e32 v79, v60, v80
	v_fmac_f32_e32 v79, v61, v81
	v_add_f32_e32 v82, v82, v79
	ds_read_b128 v[78:81], v8 offset:23984
	s_waitcnt lgkmcnt(0)
	v_mul_f32_e32 v79, v58, v79
	v_fmac_f32_e32 v79, v53, v78
	v_fmac_f32_e32 v79, v57, v80
	v_fmac_f32_e32 v79, v9, v81
	v_add_f32_e32 v78, v82, v79
	v_min_f32_e32 v79, 0, v78
	v_mul_f32_e64 v78, |v78|, s2
	v_exp_f32_e32 v78, v78
	s_nop 0
	v_add_f32_e32 v78, 1.0, v78
	v_cmp_gt_f32_e32 vcc, s1, v78
	s_nop 1
	v_cndmask_b32_e64 v80, 0, 32, vcc
	v_ldexp_f32 v78, v78, v80
	v_log_f32_e32 v78, v78
	s_nop 0
	v_mul_f32_e32 v80, 0x3f317217, v78
	v_fma_f32 v80, v78, s3, -v80
	v_fmac_f32_e32 v80, 0x3377d1cf, v78
	v_fmac_f32_e32 v80, 0x3f317217, v78
	v_cmp_lt_f32_e64 s[42:43], |v78|, s8
	s_nop 1
	v_cndmask_b32_e64 v78, v78, v80, s[42:43]
	v_cndmask_b32_e32 v80, 0, v191, vcc
	v_sub_f32_e32 v78, v78, v80
	ds_read_b128 v[80:83], v8 offset:24000
	v_sub_f32_e32 v78, v79, v78
	v_fmamk_f32 v78, v78, 0x3d800000, v77
	s_waitcnt lgkmcnt(0)
	v_mul_f32_e32 v70, v70, v81
	v_fmac_f32_e32 v70, v67, v80
	v_fmac_f32_e32 v70, v68, v82
	v_fmac_f32_e32 v70, v69, v83
	ds_read_b128 v[80:83], v8 offset:24016
	v_add_f32_e32 v67, v72, v70
	s_waitcnt lgkmcnt(0)
	v_mul_f32_e32 v66, v66, v81
	v_fmac_f32_e32 v66, v63, v80
	v_fmac_f32_e32 v66, v64, v82
	v_fmac_f32_e32 v66, v65, v83
	v_add_f32_e32 v63, v67, v66
	ds_read_b128 v[64:67], v8 offset:24032
	s_waitcnt lgkmcnt(0)
	v_mul_f32_e32 v62, v62, v65
	v_fmac_f32_e32 v62, v59, v64
	v_fmac_f32_e32 v62, v60, v66
	v_fmac_f32_e32 v62, v61, v67
	v_add_f32_e32 v59, v63, v62
	ds_read_b128 v[60:63], v8 offset:24048
	s_waitcnt lgkmcnt(0)
	v_mul_f32_e32 v58, v58, v61
	v_fmac_f32_e32 v58, v53, v60
	v_fmac_f32_e32 v58, v57, v62
	v_fmac_f32_e32 v58, v9, v63
	v_add_f32_e32 v9, v59, v58
	v_min_f32_e32 v53, 0, v9
	v_mul_f32_e64 v9, |v9|, s2
	v_exp_f32_e32 v9, v9
	s_nop 0
	v_add_f32_e32 v9, 1.0, v9
	v_cmp_gt_f32_e32 vcc, s1, v9
	s_nop 1
	v_cndmask_b32_e64 v57, 0, 32, vcc
	v_ldexp_f32 v9, v9, v57
	v_log_f32_e32 v9, v9
	s_nop 0
	v_mul_f32_e32 v57, 0x3f317217, v9
	v_fma_f32 v57, v9, s3, -v57
	v_fmac_f32_e32 v57, 0x3377d1cf, v9
	v_fmac_f32_e32 v57, 0x3f317217, v9
	v_cmp_lt_f32_e64 s[42:43], |v9|, s8
	s_nop 1
	v_cndmask_b32_e64 v9, v9, v57, s[42:43]
	v_cndmask_b32_e32 v57, 0, v191, vcc
	v_sub_f32_e32 v9, v9, v57
	v_sub_f32_e32 v9, v53, v9
	v_fmamk_f32 v9, v9, 0x3d800000, v78
	ds_write_b32 v11, v9 offset:25600
	ds_write_b16 v51, v0 offset:13312
	ds_write_b16_d16_hi v51, v0 offset:13392
	v_lshl_add_u32 v0, v50, 1, v52
	ds_write_b16 v0, v4 offset:13312
	ds_write_b16_d16_hi v0, v4 offset:13392
	ds_write_b16 v51, v1 offset:13472
	ds_write_b16_d16_hi v51, v1 offset:13552
	ds_write_b16 v0, v5 offset:13472
	ds_write_b16_d16_hi v0, v5 offset:13552
	ds_write_b16 v51, v2 offset:13632
	ds_write_b16_d16_hi v51, v2 offset:13712
	ds_write_b16 v0, v6 offset:13632
	ds_write_b16_d16_hi v0, v6 offset:13712
	ds_write_b16 v51, v3 offset:13792
	ds_write_b16_d16_hi v51, v3 offset:13872
	ds_write_b16 v0, v7 offset:13792
	ds_write_b16_d16_hi v0, v7 offset:13872
	v_cmp_lt_i32_e32 vcc, 0, v55
	v_mov_b32_e32 v2, 0
	s_waitcnt lgkmcnt(0)
	s_barrier
	s_and_saveexec_b64 s[0:1], vcc
	s_cbranch_execz .LBB0_322
	ds_read_b32 v0, v152 offset:25600
	s_waitcnt lgkmcnt(0)
	v_add_f32_e32 v2, 0, v0
	s_or_b64 exec, exec, s[0:1]
	v_cmp_lt_i32_e32 vcc, 1, v55
	s_and_saveexec_b64 s[0:1], vcc
	s_cbranch_execnz .LBB0_323

.LBB0_542:
	ds_read_b128 v[58:61], v72 offset:32768
	ds_read_b128 v[76:79], v72 offset:34816
	ds_read_b128 v[80:83], v72 offset:36864
	ds_read_b128 v[84:87], v73 offset:49152
	ds_read_b128 v[88:91], v73 offset:51200
	ds_read_b128 v[92:95], v73 offset:53248
	ds_read_b128 v[96:99], v73 offset:55296
	s_waitcnt lgkmcnt(0)
	v_mfma_f32_16x16x32_bf16 v[44:47], v[84:87], v[58:61], v[44:47]
	v_mfma_f32_16x16x32_bf16 v[28:31], v[84:87], v[76:79], v[28:31]
	v_mfma_f32_16x16x32_bf16 v[12:15], v[84:87], v[80:83], v[12:15]
	v_mfma_f32_16x16x32_bf16 v[40:43], v[88:91], v[58:61], v[40:43]
	v_mfma_f32_16x16x32_bf16 v[36:39], v[92:95], v[58:61], v[36:39]
	v_mfma_f32_16x16x32_bf16 v[32:35], v[96:99], v[58:61], v[32:35]
	v_mfma_f32_16x16x32_bf16 v[24:27], v[88:91], v[76:79], v[24:27]
	v_mfma_f32_16x16x32_bf16 v[20:23], v[92:95], v[76:79], v[20:23]
	v_mfma_f32_16x16x32_bf16 v[16:19], v[96:99], v[76:79], v[16:19]
	v_mfma_f32_16x16x32_bf16 v[8:11], v[88:91], v[80:83], v[8:11]
	v_mfma_f32_16x16x32_bf16 v[4:7], v[92:95], v[80:83], v[4:7]
	v_mfma_f32_16x16x32_bf16 v[0:3], v[96:99], v[80:83], v[0:3]
	ds_read_b128 v[58:61], v74 offset:32768
	ds_read_b128 v[76:79], v74 offset:34816
	ds_read_b128 v[80:83], v74 offset:36864
	ds_read_b128 v[84:87], v75 offset:49152
	ds_read_b128 v[88:91], v75 offset:51200
	ds_read_b128 v[92:95], v75 offset:53248
	ds_read_b128 v[96:99], v75 offset:55296
	s_waitcnt lgkmcnt(0)
	v_mfma_f32_16x16x32_bf16 v[44:47], v[84:87], v[58:61], v[44:47]
	v_mfma_f32_16x16x32_bf16 v[28:31], v[84:87], v[76:79], v[28:31]
	v_mfma_f32_16x16x32_bf16 v[12:15], v[84:87], v[80:83], v[12:15]
	v_mfma_f32_16x16x32_bf16 v[100:103], v[88:91], v[58:61], v[40:43]
	v_mfma_f32_16x16x32_bf16 v[8:11], v[88:91], v[80:83], v[8:11]
	v_mfma_f32_16x16x32_bf16 v[4:7], v[92:95], v[80:83], v[4:7]
	v_mfma_f32_16x16x32_bf16 v[0:3], v[96:99], v[80:83], v[0:3]
	v_mfma_f32_16x16x32_bf16 v[36:39], v[92:95], v[58:61], v[36:39]
	v_mfma_f32_16x16x32_bf16 v[32:35], v[96:99], v[58:61], v[32:35]
	v_mfma_f32_16x16x32_bf16 v[24:27], v[88:91], v[76:79], v[24:27]
	v_mfma_f32_16x16x32_bf16 v[20:23], v[92:95], v[76:79], v[20:23]
	v_mfma_f32_16x16x32_bf16 v[16:19], v[96:99], v[76:79], v[16:19]
	v_add_u32_e32 v160, s8, v64
	v_or_b32_e32 v160, v160, v62
	v_or_b32_e32 v161, s10, v69
	v_lshlrev_b32_e32 v161, 2, v161
	v_lshl_add_u32 v162, v160, 12, v161
	v_add_u32_e32 v163, 0x10000, v162
	v_add_u32_e32 v164, 0x20000, v162
	v_readfirstlane_b32 s1, v160
	v_readlane_b32 s42, v248, 33
	v_readlane_b32 s43, v248, 34
	s_add_i32 s0, s1, 0xfffff000
	s_lshr_b32 s0, s0, 10
	s_add_i32 s0, s0, 1
	s_cmp_lt_u32 s1, 0x1000
	s_cselect_b32 s0, 0, s0
	s_add_i32 s0, s0, s17
	s_mul_i32 s0, s0, 0x6000
	s_add_u32 s36, s24, s0
	s_addc_u32 s37, s25, 0
	s_add_u32 s36, s36, 0x15000
	s_addc_u32 s37, s37, 0
	global_load_dwordx4 v[110:113], v162, s[42:43]
	global_load_dwordx4 v[114:117], v162, s[42:43] offset:64
	global_load_dwordx4 v[118:121], v162, s[42:43] offset:128
	global_load_dwordx4 v[122:125], v162, s[42:43] offset:192
	global_load_dwordx4 v[76:79], v161, s[36:37]
	global_load_dwordx4 v[80:83], v161, s[36:37] offset:64
	global_load_dwordx4 v[84:87], v161, s[36:37] offset:128
	global_load_dwordx4 v[88:91], v161, s[36:37] offset:192
	s_add_i32 s1, s1, 16
	s_add_i32 s0, s1, 0xfffff000
	s_lshr_b32 s0, s0, 10
	s_add_i32 s0, s0, 1
	s_cmp_lt_u32 s1, 0x1000
	s_cselect_b32 s0, 0, s0
	s_add_i32 s0, s0, s17
	s_mul_i32 s0, s0, 0x6000
	s_add_u32 s36, s24, s0
	s_addc_u32 s37, s25, 0
	s_add_u32 s36, s36, 0x15000
	s_addc_u32 s37, s37, 0
	global_load_dwordx4 v[126:129], v163, s[42:43]
	global_load_dwordx4 v[130:133], v163, s[42:43] offset:64
	global_load_dwordx4 v[134:137], v163, s[42:43] offset:128
	global_load_dwordx4 v[138:141], v163, s[42:43] offset:192
	global_load_dwordx4 v[92:95], v161, s[36:37]
	global_load_dwordx4 v[96:99], v161, s[36:37] offset:64
	global_load_dwordx4 v[220:223], v161, s[36:37] offset:128
	global_load_dwordx4 v[174:177], v161, s[36:37] offset:192
	s_add_i32 s1, s1, 16
	s_add_i32 s0, s1, 0xfffff000
	s_lshr_b32 s0, s0, 10
	s_add_i32 s0, s0, 1
	s_cmp_lt_u32 s1, 0x1000
	s_cselect_b32 s0, 0, s0
	s_add_i32 s0, s0, s17
	s_mul_i32 s0, s0, 0x6000
	s_add_u32 s36, s24, s0
	s_addc_u32 s37, s25, 0
	s_add_u32 s36, s36, 0x15000
	s_addc_u32 s37, s37, 0
	global_load_dwordx4 v[142:145], v164, s[42:43]
	global_load_dwordx4 v[146:149], v164, s[42:43] offset:64
	global_load_dwordx4 v[212:215], v164, s[42:43] offset:128
	global_load_dwordx4 v[216:219], v164, s[42:43] offset:192
	global_load_dwordx4 v[178:181], v161, s[36:37]
	global_load_dwordx4 v[234:237], v161, s[36:37] offset:64
	global_load_dwordx4 v[238:241], v161, s[36:37] offset:128
	global_load_dwordx4 v[242:245], v161, s[36:37] offset:192
	s_waitcnt vmcnt(16)
	v_pk_fma_f32 v[110:111], v[44:45], v[76:77], v[110:111]
	v_pk_fma_f32 v[112:113], v[46:47], v[78:79], v[112:113]
	v_pk_fma_f32 v[114:115], v[100:101], v[80:81], v[114:115]
	v_pk_fma_f32 v[116:117], v[102:103], v[82:83], v[116:117]
	v_pk_fma_f32 v[118:119], v[36:37], v[84:85], v[118:119]
	v_pk_fma_f32 v[120:121], v[38:39], v[86:87], v[120:121]
	v_pk_fma_f32 v[122:123], v[32:33], v[88:89], v[122:123]
	v_pk_fma_f32 v[124:125], v[34:35], v[90:91], v[124:125]
	global_store_dwordx4 v162, v[110:113], s[42:43] nt
	global_store_dwordx4 v162, v[114:117], s[42:43] offset:64 nt
	global_store_dwordx4 v162, v[118:121], s[42:43] offset:128 nt
	global_store_dwordx4 v162, v[122:125], s[42:43] offset:192 nt
	s_waitcnt vmcnt(12)
	v_pk_fma_f32 v[126:127], v[28:29], v[92:93], v[126:127]
	v_pk_fma_f32 v[128:129], v[30:31], v[94:95], v[128:129]
	v_pk_fma_f32 v[130:131], v[24:25], v[96:97], v[130:131]
	v_pk_fma_f32 v[132:133], v[26:27], v[98:99], v[132:133]
	v_pk_fma_f32 v[134:135], v[20:21], v[220:221], v[134:135]
	v_pk_fma_f32 v[136:137], v[22:23], v[222:223], v[136:137]
	v_pk_fma_f32 v[138:139], v[16:17], v[174:175], v[138:139]
	v_pk_fma_f32 v[140:141], v[18:19], v[176:177], v[140:141]
	global_store_dwordx4 v163, v[126:129], s[42:43] nt
	global_store_dwordx4 v163, v[130:133], s[42:43] offset:64 nt
	global_store_dwordx4 v163, v[134:137], s[42:43] offset:128 nt
	global_store_dwordx4 v163, v[138:141], s[42:43] offset:192 nt
	s_waitcnt vmcnt(8)
	v_pk_fma_f32 v[142:143], v[12:13], v[178:179], v[142:143]
	v_pk_fma_f32 v[144:145], v[14:15], v[180:181], v[144:145]
	v_pk_fma_f32 v[146:147], v[8:9], v[234:235], v[146:147]
	v_pk_fma_f32 v[148:149], v[10:11], v[236:237], v[148:149]
	v_pk_fma_f32 v[212:213], v[4:5], v[238:239], v[212:213]
	v_pk_fma_f32 v[214:215], v[6:7], v[240:241], v[214:215]
	v_pk_fma_f32 v[216:217], v[0:1], v[242:243], v[216:217]
	v_pk_fma_f32 v[218:219], v[2:3], v[244:245], v[218:219]
	global_store_dwordx4 v164, v[142:145], s[42:43] nt
	global_store_dwordx4 v164, v[146:149], s[42:43] offset:64 nt
	global_store_dwordx4 v164, v[212:215], s[42:43] offset:128 nt
	global_store_dwordx4 v164, v[216:219], s[42:43] offset:192 nt
	s_movk_i32 s1, 0xfff
	s_movk_i32 s0, 0x1800
	v_readlane_b32 s36, v248, 27
	v_readlane_b32 s37, v248, 28
	v_readlane_b32 s38, v248, 29
	v_readlane_b32 s39, v248, 30
	v_readlane_b32 s40, v248, 31
	v_readlane_b32 s41, v248, 32
	v_readlane_b32 s42, v248, 33
	v_readlane_b32 s43, v248, 34
	s_cmp_eq_u32 s18, s16
	s_mov_b64 s[8:9], s[2:3]
	s_cbranch_scc1 .LBB0_563

.LBB0_583:
	s_cmpk_gt_u32 s22, 0x418
	s_cbranch_scc1 .Ltr_entry
	s_cmpk_gt_i32 s22, 0x17f
	s_mov_b64 s[0:1], -1
	s_cbranch_scc0 .LBB0_639
	s_cmpk_lg_i32 s22, 0x180
	s_cbranch_scc0 .LBB0_625
	s_cmpk_gt_u32 s22, 0x198
	s_cbranch_scc0 .LBB0_612
	s_cmpk_gt_u32 s22, 0x418
	s_cbranch_scc0 .LBB0_604
	s_add_i32 s0, s22, 0xfbe7
	s_and_b32 s1, s0, 0xffff
	s_mulk_i32 s1, 0x7683
	s_lshr_b32 s4, s1, 26
	s_mul_i32 s1, s4, 0x8a4
	s_sub_i32 s0, s0, s1
	s_and_b32 s5, s0, 0xffff
	s_cmpk_gt_u32 s5, 0x363
	s_mov_b64 s[0:1], -1
	s_cbranch_scc0 .LBB0_601
	s_cmpk_gt_u32 s5, 0x423
	s_cbranch_scc0 .LBB0_598
	s_cmpk_gt_u32 s5, 0x4a3
	s_cbranch_scc0 .LBB0_595
	s_lshl_b32 s7, s4, 24
	s_lshl_b32 s6, s4, 23
	s_cmpk_gt_u32 s5, 0x6a3
	s_cbranch_scc0 .LBB0_592
	v_readlane_b32 s52, v248, 27
	s_add_i32 s1, s5, 0xfffff95c
	v_readlane_b32 s56, v248, 31
	v_readlane_b32 s57, v248, 32
	s_add_u32 s8, s56, s7
	s_addc_u32 s9, s57, 0
	s_lshl_b32 s0, s1, 3
	s_lshl_b32 s1, s1, 5
	s_and_b32 s0, s0, 0x7fffff00
	s_and_b32 s1, s1, 0x3e0
	v_readlane_b32 s2, v248, 39
	s_add_u32 s2, s2, s6
	v_readlane_b32 s3, v248, 40
	s_addc_u32 s3, s3, 0
	s_lshl_b32 s10, s1, 2
	v_add_u32_e32 v0, s0, v13
	s_add_u32 s8, s8, s10
	s_addc_u32 s9, s9, 0
	v_lshlrev_b32_e32 v152, 2, v12
	v_ashrrev_i32_e32 v1, 31, v0
	v_lshl_add_u64 v[2:3], s[8:9], 0, v[152:153]
	v_lshlrev_b64 v[0:1], 12, v[0:1]
	v_lshl_add_u64 v[28:29], v[2:3], 0, v[0:1]
	s_mov_b32 s8, 0x20000
	v_add_co_u32_e32 v4, vcc, s8, v28
	global_load_dwordx4 v[0:3], v[28:29], off nt
	s_nop 0
	v_addc_co_u32_e32 v5, vcc, 0, v29, vcc
	s_mov_b32 s8, 0x40000
	global_load_dwordx4 v[4:7], v[4:5], off nt
	v_add_co_u32_e32 v24, vcc, s8, v28
	s_mov_b32 s8, 0x60000
	s_nop 0
	v_addc_co_u32_e32 v25, vcc, 0, v29, vcc
	global_load_dwordx4 v[24:27], v[24:25], off nt
	v_add_co_u32_e32 v38, vcc, s8, v28
	s_mov_b32 s8, 0x80000
	s_nop 0
	v_addc_co_u32_e32 v39, vcc, 0, v29, vcc
	global_load_dwordx4 v[38:41], v[38:39], off nt
	v_add_co_u32_e32 v42, vcc, s8, v28
	s_mov_b32 s8, 0xa0000
	s_nop 0
	v_addc_co_u32_e32 v43, vcc, 0, v29, vcc
	global_load_dwordx4 v[42:45], v[42:43], off nt
	v_add_co_u32_e32 v46, vcc, s8, v28
	s_mov_b32 s8, 0xc0000
	s_nop 0
	v_addc_co_u32_e32 v47, vcc, 0, v29, vcc
	global_load_dwordx4 v[46:49], v[46:47], off nt
	v_add_co_u32_e32 v50, vcc, s8, v28
	s_mov_b32 s8, 0xe0000
	s_nop 0
	v_addc_co_u32_e32 v51, vcc, 0, v29, vcc
	global_load_dwordx4 v[50:53], v[50:51], off nt
	v_add_co_u32_e32 v28, vcc, s8, v28
	s_lshl_b32 s12, s0, 1
	s_nop 0
	v_addc_co_u32_e32 v29, vcc, 0, v29, vcc
	global_load_dwordx4 v[54:57], v[28:29], off nt
	s_barrier
	v_lshlrev_b32_e32 v152, 1, v14
	v_readlane_b32 s53, v248, 28
	v_readlane_b32 s54, v248, 29
	v_readlane_b32 s55, v248, 30
	v_readlane_b32 s58, v248, 33
	v_readlane_b32 s59, v248, 34
	s_waitcnt vmcnt(7)
	ds_write2_b32 v30, v0, v1 offset1:1
	ds_write2_b32 v30, v2, v3 offset0:2 offset1:3
	v_add_u32_e32 v0, 0x1080, v30
	s_waitcnt vmcnt(6)
	ds_write2_b32 v0, v4, v5 offset1:1
	v_add_u32_e32 v0, 0x1088, v30
	ds_write2_b32 v0, v6, v7 offset1:1
	v_add_u32_e32 v0, 0x2100, v30
	s_waitcnt vmcnt(5)
	ds_write2_b32 v0, v24, v25 offset1:1
	v_add_u32_e32 v0, 0x2108, v30
	ds_write2_b32 v0, v26, v27 offset1:1
	v_add_u32_e32 v0, 0x3180, v30
	s_waitcnt vmcnt(4)
	ds_write2_b32 v0, v38, v39 offset1:1
	v_add_u32_e32 v0, 0x3188, v30
	ds_write2_b32 v0, v40, v41 offset1:1
	v_add_u32_e32 v0, 0x4200, v30
	s_waitcnt vmcnt(3)
	ds_write2_b32 v0, v42, v43 offset1:1
	v_add_u32_e32 v0, 0x4208, v30
	ds_write2_b32 v0, v44, v45 offset1:1
	v_add_u32_e32 v0, 0x5280, v30
	s_waitcnt vmcnt(2)
	ds_write2_b32 v0, v46, v47 offset1:1
	v_add_u32_e32 v0, 0x5288, v30
	ds_write2_b32 v0, v48, v49 offset1:1
	v_add_u32_e32 v0, 0x6300, v30
	s_waitcnt vmcnt(1)
	ds_write2_b32 v0, v50, v51 offset1:1
	v_add_u32_e32 v0, 0x6308, v30
	ds_write2_b32 v0, v52, v53 offset1:1
	v_add_u32_e32 v0, 0x7380, v30
	s_waitcnt vmcnt(0)
	ds_write2_b32 v0, v54, v55 offset1:1
	v_add_u32_e32 v0, 0x7388, v30
	ds_write2_b32 v0, v56, v57 offset1:1
	v_add_u32_e32 v0, s1, v13
	v_ashrrev_i32_e32 v1, 31, v0
	v_lshlrev_b64 v[0:1], 13, v[0:1]
	v_lshl_add_u64 v[0:1], s[2:3], 0, v[0:1]
	v_lshl_add_u64 v[0:1], v[0:1], 0, s[12:13]
	s_waitcnt lgkmcnt(0)
	s_barrier
	v_lshl_add_u64 v[4:5], v[0:1], 0, v[152:153]
	ds_read2_b32 v[0:1], v31 offset1:33
	ds_read2_b32 v[2:3], v31 offset0:66 offset1:99
	ds_read2_b32 v[6:7], v31 offset0:198 offset1:231
	s_mov_b64 s[0:1], 0
	s_waitcnt lgkmcnt(2)
	v_cvt_pk_bf16_f32 v0, v0, v1
	s_waitcnt lgkmcnt(1)
	v_cvt_pk_bf16_f32 v1, v2, v3
	ds_read2_b32 v[2:3], v31 offset0:132 offset1:165
	s_waitcnt lgkmcnt(0)
	v_cvt_pk_bf16_f32 v2, v2, v3
	v_cvt_pk_bf16_f32 v3, v6, v7
	v_add_u32_e32 v6, 0x400, v31
	global_store_dwordx4 v[4:5], v[0:3], off
	ds_read2_b32 v[0:1], v6 offset0:8 offset1:41
	ds_read2_b32 v[2:3], v6 offset0:74 offset1:107
	s_waitcnt lgkmcnt(1)
	v_cvt_pk_bf16_f32 v0, v0, v1
	s_waitcnt lgkmcnt(0)
	v_cvt_pk_bf16_f32 v1, v2, v3
	ds_read2_b32 v[2:3], v6 offset0:140 offset1:173
	ds_read2_b32 v[6:7], v6 offset0:206 offset1:239
	s_waitcnt lgkmcnt(1)
	v_cvt_pk_bf16_f32 v2, v2, v3
	s_waitcnt lgkmcnt(0)
	v_cvt_pk_bf16_f32 v3, v6, v7
	v_add_u32_e32 v6, 0x800, v31
	global_store_dwordx4 v[4:5], v[0:3], off offset:16
	ds_read2_b32 v[0:1], v6 offset0:16 offset1:49
	ds_read2_b32 v[2:3], v6 offset0:82 offset1:115
	s_waitcnt lgkmcnt(1)
	v_cvt_pk_bf16_f32 v0, v0, v1
	s_waitcnt lgkmcnt(0)
	v_cvt_pk_bf16_f32 v1, v2, v3
	ds_read2_b32 v[2:3], v6 offset0:148 offset1:181
	ds_read2_b32 v[6:7], v6 offset0:214 offset1:247
	s_waitcnt lgkmcnt(1)
	v_cvt_pk_bf16_f32 v2, v2, v3
	s_waitcnt lgkmcnt(0)
	v_cvt_pk_bf16_f32 v3, v6, v7
	v_add_u32_e32 v6, 0xc00, v31
	global_store_dwordx4 v[4:5], v[0:3], off offset:32
	ds_read2_b32 v[0:1], v6 offset0:24 offset1:57
	ds_read2_b32 v[2:3], v6 offset0:90 offset1:123
	s_waitcnt lgkmcnt(1)
	v_cvt_pk_bf16_f32 v0, v0, v1
	s_waitcnt lgkmcnt(0)
	v_cvt_pk_bf16_f32 v1, v2, v3
	ds_read2_b32 v[2:3], v6 offset0:156 offset1:189
	ds_read2_b32 v[6:7], v6 offset0:222 offset1:255
	s_waitcnt lgkmcnt(1)
	v_cvt_pk_bf16_f32 v2, v2, v3
	s_waitcnt lgkmcnt(0)
	v_cvt_pk_bf16_f32 v3, v6, v7
	global_store_dwordx4 v[4:5], v[0:3], off offset:48

.LBB0_648:
	v_readlane_b32 s52, v249, 29
	v_readlane_b32 s53, v249, 30
	s_add_u32 s52, s52, s0
	s_addc_u32 s53, s53, s1
	v_lshrrev_b32_e32 v58, 6, v167
	v_mul_u32_u24_e32 v58, 0x600000, v58
	v_and_b32_e32 v59, 63, v167
	v_lshl_add_u32 v58, v59, 2, v58
	global_load_dword v64, v58, s[52:53] nt
	s_add_u32 s52, s52, 0x6000
	s_addc_u32 s53, s53, 0
	global_load_dword v65, v58, s[52:53] nt
	s_add_u32 s52, s52, 0x6000
	s_addc_u32 s53, s53, 0
	global_load_dword v66, v58, s[52:53] nt
	s_add_u32 s52, s52, 0x6000
	s_addc_u32 s53, s53, 0
	global_load_dword v67, v58, s[52:53] nt
	s_add_u32 s52, s52, 0x6000
	s_addc_u32 s53, s53, 0
	global_load_dword v68, v58, s[52:53] nt
	s_add_u32 s52, s52, 0x6000
	s_addc_u32 s53, s53, 0
	global_load_dword v69, v58, s[52:53] nt
	s_add_u32 s52, s52, 0x6000
	s_addc_u32 s53, s53, 0
	global_load_dword v70, v58, s[52:53] nt
	s_add_u32 s52, s52, 0x6000
	s_addc_u32 s53, s53, 0
	global_load_dword v71, v58, s[52:53] nt
	s_add_u32 s52, s52, 0x6000
	s_addc_u32 s53, s53, 0
	global_load_dword v72, v58, s[52:53] nt
	s_add_u32 s52, s52, 0x6000
	s_addc_u32 s53, s53, 0
	global_load_dword v73, v58, s[52:53] nt
	s_add_u32 s52, s52, 0x6000
	s_addc_u32 s53, s53, 0
	global_load_dword v74, v58, s[52:53] nt
	s_add_u32 s52, s52, 0x6000
	s_addc_u32 s53, s53, 0
	global_load_dword v75, v58, s[52:53] nt
	s_add_u32 s52, s52, 0x6000
	s_addc_u32 s53, s53, 0
	global_load_dword v76, v58, s[52:53] nt
	s_add_u32 s52, s52, 0x6000
	s_addc_u32 s53, s53, 0
	global_load_dword v77, v58, s[52:53] nt
	s_add_u32 s52, s52, 0x6000
	s_addc_u32 s53, s53, 0
	global_load_dword v78, v58, s[52:53] nt
	s_add_u32 s52, s52, 0x6000
	s_addc_u32 s53, s53, 0
	global_load_dword v79, v58, s[52:53] nt
	s_add_u32 s52, s52, 0x6000
	s_addc_u32 s53, s53, 0
	s_mov_b32 s54, 0
.Lmod_loop:
	global_load_dword v80, v58, s[52:53] nt
	s_add_u32 s52, s52, 0x6000
	s_addc_u32 s53, s53, 0
	global_load_dword v81, v58, s[52:53] nt
	s_add_u32 s52, s52, 0x6000
	s_addc_u32 s53, s53, 0
	global_load_dword v82, v58, s[52:53] nt
	s_add_u32 s52, s52, 0x6000
	s_addc_u32 s53, s53, 0
	global_load_dword v83, v58, s[52:53] nt
	s_add_u32 s52, s52, 0x6000
	s_addc_u32 s53, s53, 0
	global_load_dword v84, v58, s[52:53] nt
	s_add_u32 s52, s52, 0x6000
	s_addc_u32 s53, s53, 0
	global_load_dword v85, v58, s[52:53] nt
	s_add_u32 s52, s52, 0x6000
	s_addc_u32 s53, s53, 0
	global_load_dword v86, v58, s[52:53] nt
	s_add_u32 s52, s52, 0x6000
	s_addc_u32 s53, s53, 0
	global_load_dword v87, v58, s[52:53] nt
	s_add_u32 s52, s52, 0x6000
	s_addc_u32 s53, s53, 0
	global_load_dword v88, v58, s[52:53] nt
	s_add_u32 s52, s52, 0x6000
	s_addc_u32 s53, s53, 0
	global_load_dword v89, v58, s[52:53] nt
	s_add_u32 s52, s52, 0x6000
	s_addc_u32 s53, s53, 0
	global_load_dword v90, v58, s[52:53] nt
	s_add_u32 s52, s52, 0x6000
	s_addc_u32 s53, s53, 0
	global_load_dword v91, v58, s[52:53] nt
	s_add_u32 s52, s52, 0x6000
	s_addc_u32 s53, s53, 0
	global_load_dword v92, v58, s[52:53] nt
	s_add_u32 s52, s52, 0x6000
	s_addc_u32 s53, s53, 0
	global_load_dword v93, v58, s[52:53] nt
	s_add_u32 s52, s52, 0x6000
	s_addc_u32 s53, s53, 0
	global_load_dword v94, v58, s[52:53] nt
	s_add_u32 s52, s52, 0x6000
	s_addc_u32 s53, s53, 0
	global_load_dword v95, v58, s[52:53] nt
	s_add_u32 s52, s52, 0x6000
	s_addc_u32 s53, s53, 0
	ds_read_b128 v[96:99], v37 offset:0
	ds_read_b128 v[100:103], v37 offset:16
	ds_read_b128 v[104:107], v37 offset:32
	ds_read_b128 v[108:111], v37 offset:48
	ds_read_b128 v[112:115], v37 offset:4096
	ds_read_b128 v[116:119], v37 offset:4112
	ds_read_b128 v[120:123], v37 offset:4128
	ds_read_b128 v[124:127], v37 offset:4144
	ds_read_b128 v[128:131], v37 offset:8192
	ds_read_b128 v[132:135], v37 offset:8208
	ds_read_b128 v[136:139], v37 offset:8224
	ds_read_b128 v[140:143], v37 offset:8240
	v_add_u32_e32 v37, 64, v37
	s_waitcnt vmcnt(16)
	s_waitcnt lgkmcnt(0)
	v_fmac_f32_e32 v28, v64, v96
	v_fmac_f32_e32 v29, v64, v112
	v_fmac_f32_e32 v17, v64, v128
	v_fmac_f32_e32 v28, v65, v97
	v_fmac_f32_e32 v29, v65, v113
	v_fmac_f32_e32 v17, v65, v129
	v_fmac_f32_e32 v28, v66, v98
	v_fmac_f32_e32 v29, v66, v114
	v_fmac_f32_e32 v17, v66, v130
	v_fmac_f32_e32 v28, v67, v99
	v_fmac_f32_e32 v29, v67, v115
	v_fmac_f32_e32 v17, v67, v131
	v_fmac_f32_e32 v28, v68, v100
	v_fmac_f32_e32 v29, v68, v116
	v_fmac_f32_e32 v17, v68, v132
	v_fmac_f32_e32 v28, v69, v101
	v_fmac_f32_e32 v29, v69, v117
	v_fmac_f32_e32 v17, v69, v133
	v_fmac_f32_e32 v28, v70, v102
	v_fmac_f32_e32 v29, v70, v118
	v_fmac_f32_e32 v17, v70, v134
	v_fmac_f32_e32 v28, v71, v103
	v_fmac_f32_e32 v29, v71, v119
	v_fmac_f32_e32 v17, v71, v135
	v_fmac_f32_e32 v28, v72, v104
	v_fmac_f32_e32 v29, v72, v120
	v_fmac_f32_e32 v17, v72, v136
	v_fmac_f32_e32 v28, v73, v105
	v_fmac_f32_e32 v29, v73, v121
	v_fmac_f32_e32 v17, v73, v137
	v_fmac_f32_e32 v28, v74, v106
	v_fmac_f32_e32 v29, v74, v122
	v_fmac_f32_e32 v17, v74, v138
	v_fmac_f32_e32 v28, v75, v107
	v_fmac_f32_e32 v29, v75, v123
	v_fmac_f32_e32 v17, v75, v139
	v_fmac_f32_e32 v28, v76, v108
	v_fmac_f32_e32 v29, v76, v124
	v_fmac_f32_e32 v17, v76, v140
	v_fmac_f32_e32 v28, v77, v109
	v_fmac_f32_e32 v29, v77, v125
	v_fmac_f32_e32 v17, v77, v141
	v_fmac_f32_e32 v28, v78, v110
	v_fmac_f32_e32 v29, v78, v126
	v_fmac_f32_e32 v17, v78, v142
	v_fmac_f32_e32 v28, v79, v111
	v_fmac_f32_e32 v29, v79, v127
	v_fmac_f32_e32 v17, v79, v143
	s_add_i32 s54, s54, 1
	s_cmp_eq_u32 s54, 8
	s_cbranch_scc1 .Lmod_tail
	global_load_dword v64, v58, s[52:53] nt
	s_add_u32 s52, s52, 0x6000
	s_addc_u32 s53, s53, 0
	global_load_dword v65, v58, s[52:53] nt
	s_add_u32 s52, s52, 0x6000
	s_addc_u32 s53, s53, 0
	global_load_dword v66, v58, s[52:53] nt
	s_add_u32 s52, s52, 0x6000
	s_addc_u32 s53, s53, 0
	global_load_dword v67, v58, s[52:53] nt
	s_add_u32 s52, s52, 0x6000
	s_addc_u32 s53, s53, 0
	global_load_dword v68, v58, s[52:53] nt
	s_add_u32 s52, s52, 0x6000
	s_addc_u32 s53, s53, 0
	global_load_dword v69, v58, s[52:53] nt
	s_add_u32 s52, s52, 0x6000
	s_addc_u32 s53, s53, 0
	global_load_dword v70, v58, s[52:53] nt
	s_add_u32 s52, s52, 0x6000
	s_addc_u32 s53, s53, 0
	global_load_dword v71, v58, s[52:53] nt
	s_add_u32 s52, s52, 0x6000
	s_addc_u32 s53, s53, 0
	global_load_dword v72, v58, s[52:53] nt
	s_add_u32 s52, s52, 0x6000
	s_addc_u32 s53, s53, 0
	global_load_dword v73, v58, s[52:53] nt
	s_add_u32 s52, s52, 0x6000
	s_addc_u32 s53, s53, 0
	global_load_dword v74, v58, s[52:53] nt
	s_add_u32 s52, s52, 0x6000
	s_addc_u32 s53, s53, 0
	global_load_dword v75, v58, s[52:53] nt
	s_add_u32 s52, s52, 0x6000
	s_addc_u32 s53, s53, 0
	global_load_dword v76, v58, s[52:53] nt
	s_add_u32 s52, s52, 0x6000
	s_addc_u32 s53, s53, 0
	global_load_dword v77, v58, s[52:53] nt
	s_add_u32 s52, s52, 0x6000
	s_addc_u32 s53, s53, 0
	global_load_dword v78, v58, s[52:53] nt
	s_add_u32 s52, s52, 0x6000
	s_addc_u32 s53, s53, 0
	global_load_dword v79, v58, s[52:53] nt
	s_add_u32 s52, s52, 0x6000
	s_addc_u32 s53, s53, 0
	ds_read_b128 v[96:99], v37 offset:0
	ds_read_b128 v[100:103], v37 offset:16
	ds_read_b128 v[104:107], v37 offset:32
	ds_read_b128 v[108:111], v37 offset:48
	ds_read_b128 v[112:115], v37 offset:4096
	ds_read_b128 v[116:119], v37 offset:4112
	ds_read_b128 v[120:123], v37 offset:4128
	ds_read_b128 v[124:127], v37 offset:4144
	ds_read_b128 v[128:131], v37 offset:8192
	ds_read_b128 v[132:135], v37 offset:8208
	ds_read_b128 v[136:139], v37 offset:8224
	ds_read_b128 v[140:143], v37 offset:8240
	v_add_u32_e32 v37, 64, v37
	s_waitcnt vmcnt(16)
	s_waitcnt lgkmcnt(0)
	v_fmac_f32_e32 v28, v80, v96
	v_fmac_f32_e32 v29, v80, v112
	v_fmac_f32_e32 v17, v80, v128
	v_fmac_f32_e32 v28, v81, v97
	v_fmac_f32_e32 v29, v81, v113
	v_fmac_f32_e32 v17, v81, v129
	v_fmac_f32_e32 v28, v82, v98
	v_fmac_f32_e32 v29, v82, v114
	v_fmac_f32_e32 v17, v82, v130
	v_fmac_f32_e32 v28, v83, v99
	v_fmac_f32_e32 v29, v83, v115
	v_fmac_f32_e32 v17, v83, v131
	v_fmac_f32_e32 v28, v84, v100
	v_fmac_f32_e32 v29, v84, v116
	v_fmac_f32_e32 v17, v84, v132
	v_fmac_f32_e32 v28, v85, v101
	v_fmac_f32_e32 v29, v85, v117
	v_fmac_f32_e32 v17, v85, v133
	v_fmac_f32_e32 v28, v86, v102
	v_fmac_f32_e32 v29, v86, v118
	v_fmac_f32_e32 v17, v86, v134
	v_fmac_f32_e32 v28, v87, v103
	v_fmac_f32_e32 v29, v87, v119
	v_fmac_f32_e32 v17, v87, v135
	v_fmac_f32_e32 v28, v88, v104
	v_fmac_f32_e32 v29, v88, v120
	v_fmac_f32_e32 v17, v88, v136
	v_fmac_f32_e32 v28, v89, v105
	v_fmac_f32_e32 v29, v89, v121
	v_fmac_f32_e32 v17, v89, v137
	v_fmac_f32_e32 v28, v90, v106
	v_fmac_f32_e32 v29, v90, v122
	v_fmac_f32_e32 v17, v90, v138
	v_fmac_f32_e32 v28, v91, v107
	v_fmac_f32_e32 v29, v91, v123
	v_fmac_f32_e32 v17, v91, v139
	v_fmac_f32_e32 v28, v92, v108
	v_fmac_f32_e32 v29, v92, v124
	v_fmac_f32_e32 v17, v92, v140
	v_fmac_f32_e32 v28, v93, v109
	v_fmac_f32_e32 v29, v93, v125
	v_fmac_f32_e32 v17, v93, v141
	v_fmac_f32_e32 v28, v94, v110
	v_fmac_f32_e32 v29, v94, v126
	v_fmac_f32_e32 v17, v94, v142
	v_fmac_f32_e32 v28, v95, v111
	v_fmac_f32_e32 v29, v95, v127
	v_fmac_f32_e32 v17, v95, v143
	s_branch .Lmod_loop
.Lmod_tail:
	ds_read_b128 v[96:99], v37 offset:0
	ds_read_b128 v[100:103], v37 offset:16
	ds_read_b128 v[104:107], v37 offset:32
	ds_read_b128 v[108:111], v37 offset:48
	ds_read_b128 v[112:115], v37 offset:4096
	ds_read_b128 v[116:119], v37 offset:4112
	ds_read_b128 v[120:123], v37 offset:4128
	ds_read_b128 v[124:127], v37 offset:4144
	ds_read_b128 v[128:131], v37 offset:8192
	ds_read_b128 v[132:135], v37 offset:8208
	ds_read_b128 v[136:139], v37 offset:8224
	ds_read_b128 v[140:143], v37 offset:8240
	v_add_u32_e32 v37, 64, v37
	s_waitcnt vmcnt(0)
	s_waitcnt lgkmcnt(0)
	v_fmac_f32_e32 v28, v80, v96
	v_fmac_f32_e32 v29, v80, v112
	v_fmac_f32_e32 v17, v80, v128
	v_fmac_f32_e32 v28, v81, v97
	v_fmac_f32_e32 v29, v81, v113
	v_fmac_f32_e32 v17, v81, v129
	v_fmac_f32_e32 v28, v82, v98
	v_fmac_f32_e32 v29, v82, v114
	v_fmac_f32_e32 v17, v82, v130
	v_fmac_f32_e32 v28, v83, v99
	v_fmac_f32_e32 v29, v83, v115
	v_fmac_f32_e32 v17, v83, v131
	v_fmac_f32_e32 v28, v84, v100
	v_fmac_f32_e32 v29, v84, v116
	v_fmac_f32_e32 v17, v84, v132
	v_fmac_f32_e32 v28, v85, v101
	v_fmac_f32_e32 v29, v85, v117
	v_fmac_f32_e32 v17, v85, v133
	v_fmac_f32_e32 v28, v86, v102
	v_fmac_f32_e32 v29, v86, v118
	v_fmac_f32_e32 v17, v86, v134
	v_fmac_f32_e32 v28, v87, v103
	v_fmac_f32_e32 v29, v87, v119
	v_fmac_f32_e32 v17, v87, v135
	v_fmac_f32_e32 v28, v88, v104
	v_fmac_f32_e32 v29, v88, v120
	v_fmac_f32_e32 v17, v88, v136
	v_fmac_f32_e32 v28, v89, v105
	v_fmac_f32_e32 v29, v89, v121
	v_fmac_f32_e32 v17, v89, v137
	v_fmac_f32_e32 v28, v90, v106
	v_fmac_f32_e32 v29, v90, v122
	v_fmac_f32_e32 v17, v90, v138
	v_fmac_f32_e32 v28, v91, v107
	v_fmac_f32_e32 v29, v91, v123
	v_fmac_f32_e32 v17, v91, v139
	v_fmac_f32_e32 v28, v92, v108
	v_fmac_f32_e32 v29, v92, v124
	v_fmac_f32_e32 v17, v92, v140
	v_fmac_f32_e32 v28, v93, v109
	v_fmac_f32_e32 v29, v93, v125
	v_fmac_f32_e32 v17, v93, v141
	v_fmac_f32_e32 v28, v94, v110
	v_fmac_f32_e32 v29, v94, v126
	v_fmac_f32_e32 v17, v94, v142
	v_fmac_f32_e32 v28, v95, v111
	v_fmac_f32_e32 v29, v95, v127
	v_fmac_f32_e32 v17, v95, v143
	s_barrier
	ds_write2st64_b32 v32, v28, v29 offset0:48 offset1:49
	ds_write_b32 v32, v17 offset:12800
	s_waitcnt lgkmcnt(0)
	s_barrier
	s_and_saveexec_b64 s[0:1], s[46:47]
	s_cbranch_execz .LBB0_581
	s_mul_i32 s3, s6, 0x1800
	s_add_i32 s3, s3, s2
	v_or_b32_e32 v0, s3, v11
	v_readlane_b32 s52, v249, 25
	v_ashrrev_i32_e32 v1, 31, v0
	v_readlane_b32 s58, v249, 31
	v_readlane_b32 s59, v249, 32
	s_movk_i32 s3, 0x1800
	v_readlane_b32 s53, v249, 26
	v_lshl_add_u64 v[0:1], v[0:1], 2, s[58:59]
	global_load_dword v2, v[0:1], off
	ds_read2st64_b32 v[0:1], v34 offset0:48 offset1:51
	v_readlane_b32 s54, v249, 27
	v_readlane_b32 s55, v249, 28
	v_readlane_b32 s56, v249, 29
	v_readlane_b32 s57, v249, 30
	s_waitcnt vmcnt(0) lgkmcnt(0)
	v_add_f32_e32 v0, v2, v0
	v_add_f32_e32 v2, v0, v1
	ds_read2st64_b32 v[0:1], v34 offset0:54 offset1:57
	s_waitcnt lgkmcnt(0)
	v_add_f32_e32 v0, v2, v0
	v_add_f32_e32 v2, v0, v1
	v_mad_u64_u32 v[0:1], s[4:5], s6, 3, v[10:11]
	v_mul_lo_u32 v0, v0, s3
	v_add_u32_e32 v0, s2, v0
	v_or_b32_e32 v0, v0, v11
	v_readlane_b32 s2, v248, 37
	v_ashrrev_i32_e32 v1, 31, v0
	v_readlane_b32 s3, v248, 38
	s_nop 1
	v_lshl_add_u64 v[0:1], v[0:1], 2, s[2:3]
	global_store_dword v[0:1], v2, off
	s_branch .LBB0_581
.Ltr_entry:
	v_mov_b32_e32 v0, v167
	v_lshrrev_b32_e32 v14, 3, v0
	v_and_b32_e32 v15, 7, v0
	v_lshrrev_b32_e32 v16, 5, v0
	v_and_b32_e32 v17, 31, v0
	v_lshrrev_b32_e32 v18, 3, v14
	v_xor_b32_e32 v18, v18, v15
	v_lshlrev_b32_e32 v18, 4, v18
	v_and_b32_e32 v19, 7, v14
	v_lshl_add_u32 v18, v19, 1, v18
	v_lshl_add_u32 v7, v15, 11, v18
	v_add_u32_e32 v18, 0, v16
	v_lshrrev_b32_e32 v19, 2, v18
	v_xor_b32_e32 v19, v19, v17
	v_lshlrev_b32_e32 v19, 4, v19
	v_lshl_add_u32 v8, v18, 9, v19
	v_add_u32_e32 v18, 8, v16
	v_lshrrev_b32_e32 v19, 2, v18
	v_xor_b32_e32 v19, v19, v17
	v_lshlrev_b32_e32 v19, 4, v19
	v_lshl_add_u32 v9, v18, 9, v19
	v_add_u32_e32 v18, 16, v16
	v_lshrrev_b32_e32 v19, 2, v18
	v_xor_b32_e32 v19, v19, v17
	v_lshlrev_b32_e32 v19, 4, v19
	v_lshl_add_u32 v10, v18, 9, v19
	v_add_u32_e32 v18, 24, v16
	v_lshrrev_b32_e32 v19, 2, v18
	v_xor_b32_e32 v19, v19, v17
	v_lshlrev_b32_e32 v19, 4, v19
	v_lshl_add_u32 v11, v18, 9, v19
	v_lshlrev_b32_e32 v15, 4, v15
	v_lshlrev_b32_e32 v17, 4, v17
	v_readlane_b32 s0, v249, 1
	v_readlane_b32 s1, v249, 2
	s_load_dwordx4 s[16:19], s[0:1], 0xc8
	s_load_dwordx2 s[14:15], s[0:1], 0xd8
	v_readlane_b32 s2, v249, 7
	v_readlane_b32 s3, v249, 8
	s_load_dword s24, s[2:3], 0x0
	s_waitcnt lgkmcnt(0)
	s_add_i32 s0, s22, 0xfffffbe7
	s_mov_b32 s1, 0
	s_cmpk_ge_u32 s0, 0x8a4
	s_cbranch_scc0 .Ltr_l0
	s_addk_i32 s0, 0xf75c
	s_add_i32 s1, s1, 1
	s_cmpk_ge_u32 s0, 0x8a4
	s_cbranch_scc0 .Ltr_l0
	s_addk_i32 s0, 0xf75c
	s_add_i32 s1, s1, 1
	s_cmpk_ge_u32 s0, 0x8a4
	s_cbranch_scc0 .Ltr_l0
	s_addk_i32 s0, 0xf75c
	s_add_i32 s1, s1, 1
.Ltr_l0:
	s_cmpk_lt_u32 s0, 0x364
	s_cbranch_scc0 .Ltr_k1_0
	s_mov_b32 s2, 0
	s_cmpk_ge_u32 s0, 0xd9
	s_cbranch_scc0 .Ltr_w0
	s_addk_i32 s0, 0xff27
	s_add_i32 s2, s2, 1
	s_cmpk_ge_u32 s0, 0xd9
	s_cbranch_scc0 .Ltr_w0
	s_addk_i32 s0, 0xff27
	s_add_i32 s2, s2, 1
	s_cmpk_ge_u32 s0, 0xd9
	s_cbranch_scc0 .Ltr_w0
	s_addk_i32 s0, 0xff27
	s_add_i32 s2, s2, 1
.Ltr_w0:
	s_lshl_b32 s3, s0, 5
	s_mul_i32 s4, s2, 0x6c8000
	s_lshl_b32 s5, s3, 2
	s_add_i32 s4, s4, s5
	s_mul_i32 s5, s1, 0x1b20000
	s_add_i32 s4, s4, s5
	v_readlane_b32 s6, v249, 13
	v_readlane_b32 s7, v249, 14
	s_add_u32 s40, s6, s4
	s_addc_u32 s41, s7, 0
	s_mov_b32 s42, 0xd9000
	s_movk_i32 s43, 0x6c80
	s_cmpk_lt_u32 s3, 0x620
	s_cselect_b32 s5, 0, 0x60
	s_add_i32 s3, s3, s5
	s_lshl_b32 s3, s3, 11
	s_lshl_b32 s5, s2, 9
	s_add_i32 s3, s3, s5
	s_mul_i32 s5, s1, 0xdc0000
	s_add_i32 s3, s3, s5
	s_add_i32 s3, s3, 0x100000
	s_movk_i32 s46, 0x4000
	s_movk_i32 s47, 0x800
	s_branch .Ltr_dd0
.Ltr_k1_0:
	s_cmpk_lt_u32 s0, 0x424
	s_cbranch_scc0 .Ltr_k2_0
	s_addk_i32 s0, 0xfc9c
	s_lshr_b32 s2, s0, 6
	s_bfe_u32 s3, s0, 0x10005
	s_and_b32 s0, s0, 31
	s_lshl_b32 s4, s3, 20
	s_lshl_b32 s5, s0, 7
	s_add_i32 s4, s4, s5
	s_lshl_b32 s5, s1, 21
	s_add_i32 s4, s4, s5
	s_cmp_eq_u32 s2, 0
	s_cselect_b32 s6, s16, s18
	s_cselect_b32 s7, s17, s19
	s_cmp_eq_u32 s2, 2
	s_cselect_b32 s6, s14, s6
	s_cselect_b32 s7, s15, s7
	s_add_u32 s40, s6, s4
	s_addc_u32 s41, s7, 0
	s_mov_b32 s42, 0x20000
	s_movk_i32 s43, 0x1000
	s_mul_i32 s5, s1, 3
	s_add_i32 s5, s5, s2
	s_lshl_b32 s5, s5, 20
	s_lshl_b32 s6, s0, 15
	s_add_i32 s5, s5, s6
	s_lshl_b32 s6, s3, 9
	s_add_i32 s5, s5, s6
	s_add_i32 s3, s5, 0x3800000
	s_movk_i32 s46, 0x2000
	s_movk_i32 s47, 0x400
	s_branch .Ltr_dd0
.Ltr_k2_0:
	s_cmpk_lt_u32 s0, 0x4a4
	s_cbranch_scc0 .Ltr_k3_0
	s_addk_i32 s0, 0xfbdc
	s_lshr_b32 s3, s0, 5
	s_and_b32 s0, s0, 31
	s_lshl_b32 s4, s3, 20
	s_lshl_b32 s5, s0, 7
	s_add_i32 s4, s4, s5
	s_lshl_b32 s5, s1, 22
	s_add_i32 s4, s4, s5
	v_readlane_b32 s6, v248, 27
	v_readlane_b32 s7, v248, 28
	s_add_u32 s40, s6, s4
	s_addc_u32 s41, s7, 0
	s_mov_b32 s42, 0x20000
	s_movk_i32 s43, 0x1000
	s_lshl_b32 s5, s1, 21
	s_lshl_b32 s6, s0, 16
	s_add_i32 s5, s5, s6
	s_lshl_b32 s6, s3, 9
	s_add_i32 s5, s5, s6
	s_add_i32 s3, s5, 0x4400000
	s_movk_i32 s46, 0x4000
	s_movk_i32 s47, 0x800
	s_branch .Ltr_dd0
.Ltr_k3_0:
	s_cmpk_lt_u32 s0, 0x6a4
	s_cbranch_scc0 .Ltr_k4_0
	s_addk_i32 s0, 0xfb5c
	s_lshr_b32 s3, s0, 7
	s_and_b32 s0, s0, 127
	s_lshl_b32 s4, s3, 22
	s_lshl_b32 s5, s0, 7
	s_add_i32 s4, s4, s5
	s_lshl_b32 s5, s1, 24
	s_add_i32 s4, s4, s5
	v_readlane_b32 s6, v248, 29
	v_readlane_b32 s7, v248, 30
	s_add_u32 s40, s6, s4
	s_addc_u32 s41, s7, 0
	s_mov_b32 s42, 0x80000
	s_movk_i32 s43, 0x4000
	s_lshl_b32 s5, s1, 23
	s_lshl_b32 s6, s0, 16
	s_add_i32 s5, s5, s6
	s_lshl_b32 s6, s3, 9
	s_add_i32 s5, s5, s6
	s_add_i32 s3, s5, 0x4c00000
	s_movk_i32 s46, 0x4000
	s_movk_i32 s47, 0x800
	s_branch .Ltr_dd0
.Ltr_k4_0:
	s_addk_i32 s0, 0xf95c
	s_lshr_b32 s3, s0, 5
	s_and_b32 s0, s0, 31
	s_lshl_b32 s4, s3, 20
	s_lshl_b32 s5, s0, 7
	s_add_i32 s4, s4, s5
	s_lshl_b32 s5, s1, 24
	s_add_i32 s4, s4, s5
	v_readlane_b32 s6, v248, 31
	v_readlane_b32 s7, v248, 32
	s_add_u32 s40, s6, s4
	s_addc_u32 s41, s7, 0
	s_mov_b32 s42, 0x20000
	s_movk_i32 s43, 0x1000
	s_lshl_b32 s5, s1, 23
	s_lshl_b32 s6, s0, 18
	s_add_i32 s5, s5, s6
	s_lshl_b32 s6, s3, 9
	s_add_i32 s5, s5, s6
	s_add_i32 s3, s5, 0x6c00000
	s_mov_b32 s46, 0x10000
	s_movk_i32 s47, 0x2000
.Ltr_dd0:
	v_readlane_b32 s6, v247, 39
	v_readlane_b32 s7, v247, 40
	s_add_u32 s44, s6, s3
	s_addc_u32 s45, s7, 0
	v_mul_lo_u32 v12, v14, s43
	v_add_u32_e32 v12, v12, v15
	s_mov_b32 s4, s40
	s_mov_b32 s5, s41
	global_load_dwordx4 v[64:67], v12, s[4:5] nt
	s_add_u32 s4, s4, s42
	s_addc_u32 s5, s5, 0
	global_load_dwordx4 v[68:71], v12, s[4:5] nt
	s_add_u32 s4, s4, s42
	s_addc_u32 s5, s5, 0
	global_load_dwordx4 v[72:75], v12, s[4:5] nt
	s_add_u32 s4, s4, s42
	s_addc_u32 s5, s5, 0
	global_load_dwordx4 v[76:79], v12, s[4:5] nt
	s_add_u32 s4, s4, s42
	s_addc_u32 s5, s5, 0
	global_load_dwordx4 v[80:83], v12, s[4:5] nt
	s_add_u32 s4, s4, s42
	s_addc_u32 s5, s5, 0
	global_load_dwordx4 v[84:87], v12, s[4:5] nt
	s_add_u32 s4, s4, s42
	s_addc_u32 s5, s5, 0
	global_load_dwordx4 v[88:91], v12, s[4:5] nt
	s_add_u32 s4, s4, s42
	s_addc_u32 s5, s5, 0
	global_load_dwordx4 v[92:95], v12, s[4:5] nt
	s_add_i32 s22, s22, s24
	s_cmpk_gt_i32 s22, 0x26a8
	s_cbranch_scc1 .Ltr_onlyA
	s_add_i32 s0, s22, 0xfffffbe7
	s_mov_b32 s1, 0
	s_cmpk_ge_u32 s0, 0x8a4
	s_cbranch_scc0 .Ltr_l1
	s_addk_i32 s0, 0xf75c
	s_add_i32 s1, s1, 1
	s_cmpk_ge_u32 s0, 0x8a4
	s_cbranch_scc0 .Ltr_l1
	s_addk_i32 s0, 0xf75c
	s_add_i32 s1, s1, 1
	s_cmpk_ge_u32 s0, 0x8a4
	s_cbranch_scc0 .Ltr_l1
	s_addk_i32 s0, 0xf75c
	s_add_i32 s1, s1, 1

.Ltr_w1:
	s_lshl_b32 s3, s0, 5
	s_mul_i32 s4, s2, 0x6c8000
	s_lshl_b32 s5, s3, 2
	s_add_i32 s4, s4, s5
	s_mul_i32 s5, s1, 0x1b20000
	s_add_i32 s4, s4, s5
	v_readlane_b32 s6, v249, 13
	v_readlane_b32 s7, v249, 14
	s_add_u32 s48, s6, s4
	s_addc_u32 s49, s7, 0
	s_mov_b32 s50, 0xd9000
	s_movk_i32 s51, 0x6c80
	s_cmpk_lt_u32 s3, 0x620
	s_cselect_b32 s5, 0, 0x60
	s_add_i32 s3, s3, s5
	s_lshl_b32 s3, s3, 11
	s_lshl_b32 s5, s2, 9
	s_add_i32 s3, s3, s5
	s_mul_i32 s5, s1, 0xdc0000
	s_add_i32 s3, s3, s5
	s_add_i32 s3, s3, 0x100000
	s_movk_i32 s54, 0x4000
	s_movk_i32 s55, 0x800
	s_branch .Ltr_dd1
.Ltr_k1_1:
	s_cmpk_lt_u32 s0, 0x424
	s_cbranch_scc0 .Ltr_k2_1
	s_addk_i32 s0, 0xfc9c
	s_lshr_b32 s2, s0, 6
	s_bfe_u32 s3, s0, 0x10005
	s_and_b32 s0, s0, 31
	s_lshl_b32 s4, s3, 20
	s_lshl_b32 s5, s0, 7
	s_add_i32 s4, s4, s5
	s_lshl_b32 s5, s1, 21
	s_add_i32 s4, s4, s5
	s_cmp_eq_u32 s2, 0
	s_cselect_b32 s6, s16, s18
	s_cselect_b32 s7, s17, s19
	s_cmp_eq_u32 s2, 2
	s_cselect_b32 s6, s14, s6
	s_cselect_b32 s7, s15, s7
	s_add_u32 s48, s6, s4
	s_addc_u32 s49, s7, 0
	s_mov_b32 s50, 0x20000
	s_movk_i32 s51, 0x1000
	s_mul_i32 s5, s1, 3
	s_add_i32 s5, s5, s2
	s_lshl_b32 s5, s5, 20
	s_lshl_b32 s6, s0, 15
	s_add_i32 s5, s5, s6
	s_lshl_b32 s6, s3, 9
	s_add_i32 s5, s5, s6
	s_add_i32 s3, s5, 0x3800000
	s_movk_i32 s54, 0x2000
	s_movk_i32 s55, 0x400
	s_branch .Ltr_dd1
.Ltr_k2_1:
	s_cmpk_lt_u32 s0, 0x4a4
	s_cbranch_scc0 .Ltr_k3_1
	s_addk_i32 s0, 0xfbdc
	s_lshr_b32 s3, s0, 5
	s_and_b32 s0, s0, 31
	s_lshl_b32 s4, s3, 20
	s_lshl_b32 s5, s0, 7
	s_add_i32 s4, s4, s5
	s_lshl_b32 s5, s1, 22
	s_add_i32 s4, s4, s5
	v_readlane_b32 s6, v248, 27
	v_readlane_b32 s7, v248, 28
	s_add_u32 s48, s6, s4
	s_addc_u32 s49, s7, 0
	s_mov_b32 s50, 0x20000
	s_movk_i32 s51, 0x1000
	s_lshl_b32 s5, s1, 21
	s_lshl_b32 s6, s0, 16
	s_add_i32 s5, s5, s6
	s_lshl_b32 s6, s3, 9
	s_add_i32 s5, s5, s6
	s_add_i32 s3, s5, 0x4400000
	s_movk_i32 s54, 0x4000
	s_movk_i32 s55, 0x800
	s_branch .Ltr_dd1
.Ltr_k3_1:
	s_cmpk_lt_u32 s0, 0x6a4
	s_cbranch_scc0 .Ltr_k4_1
	s_addk_i32 s0, 0xfb5c
	s_lshr_b32 s3, s0, 7
	s_and_b32 s0, s0, 127
	s_lshl_b32 s4, s3, 22
	s_lshl_b32 s5, s0, 7
	s_add_i32 s4, s4, s5
	s_lshl_b32 s5, s1, 24
	s_add_i32 s4, s4, s5
	v_readlane_b32 s6, v248, 29
	v_readlane_b32 s7, v248, 30
	s_add_u32 s48, s6, s4
	s_addc_u32 s49, s7, 0
	s_mov_b32 s50, 0x80000
	s_movk_i32 s51, 0x4000
	s_lshl_b32 s5, s1, 23
	s_lshl_b32 s6, s0, 16
	s_add_i32 s5, s5, s6
	s_lshl_b32 s6, s3, 9
	s_add_i32 s5, s5, s6
	s_add_i32 s3, s5, 0x4c00000
	s_movk_i32 s54, 0x4000
	s_movk_i32 s55, 0x800
	s_branch .Ltr_dd1
.Ltr_k4_1:
	s_addk_i32 s0, 0xf95c
	s_lshr_b32 s3, s0, 5
	s_and_b32 s0, s0, 31
	s_lshl_b32 s4, s3, 20
	s_lshl_b32 s5, s0, 7
	s_add_i32 s4, s4, s5
	s_lshl_b32 s5, s1, 24
	s_add_i32 s4, s4, s5
	v_readlane_b32 s6, v248, 31
	v_readlane_b32 s7, v248, 32
	s_add_u32 s48, s6, s4
	s_addc_u32 s49, s7, 0
	s_mov_b32 s50, 0x20000
	s_movk_i32 s51, 0x1000
	s_lshl_b32 s5, s1, 23
	s_lshl_b32 s6, s0, 18
	s_add_i32 s5, s5, s6
	s_lshl_b32 s6, s3, 9
	s_add_i32 s5, s5, s6
	s_add_i32 s3, s5, 0x6c00000
	s_mov_b32 s54, 0x10000
	s_movk_i32 s55, 0x2000
.Ltr_dd1:
	v_readlane_b32 s6, v247, 39
	v_readlane_b32 s7, v247, 40
	s_add_u32 s52, s6, s3
	s_addc_u32 s53, s7, 0
	v_mul_lo_u32 v12, v14, s51
	v_add_u32_e32 v12, v12, v15
	s_mov_b32 s4, s48
	s_mov_b32 s5, s49
	global_load_dwordx4 v[96:99], v12, s[4:5] nt
	s_add_u32 s4, s4, s50
	s_addc_u32 s5, s5, 0
	global_load_dwordx4 v[100:103], v12, s[4:5] nt
	s_add_u32 s4, s4, s50
	s_addc_u32 s5, s5, 0
	global_load_dwordx4 v[104:107], v12, s[4:5] nt
	s_add_u32 s4, s4, s50
	s_addc_u32 s5, s5, 0
	global_load_dwordx4 v[108:111], v12, s[4:5] nt
	s_add_u32 s4, s4, s50
	s_addc_u32 s5, s5, 0
	global_load_dwordx4 v[112:115], v12, s[4:5] nt
	s_add_u32 s4, s4, s50
	s_addc_u32 s5, s5, 0
	global_load_dwordx4 v[116:119], v12, s[4:5] nt
	s_add_u32 s4, s4, s50
	s_addc_u32 s5, s5, 0
	global_load_dwordx4 v[120:123], v12, s[4:5] nt
	s_add_u32 s4, s4, s50
	s_addc_u32 s5, s5, 0
	global_load_dwordx4 v[124:127], v12, s[4:5] nt
	s_waitcnt vmcnt(8)
	s_barrier
	v_xor_b32_e32 v20, 0x0, v7
	v_cvt_pk_bf16_f32 v21, v64, v65
	v_cvt_pk_bf16_f32 v22, v66, v67
	ds_write_b16 v20, v21
	ds_write_b16_d16_hi v20, v21 offset:512
	ds_write_b16 v20, v22 offset:1024
	ds_write_b16_d16_hi v20, v22 offset:1536
	v_xor_b32_e32 v20, 0x40, v7
	v_cvt_pk_bf16_f32 v21, v68, v69
	v_cvt_pk_bf16_f32 v22, v70, v71
	ds_write_b16 v20, v21
	ds_write_b16_d16_hi v20, v21 offset:512
	ds_write_b16 v20, v22 offset:1024
	ds_write_b16_d16_hi v20, v22 offset:1536
	v_xor_b32_e32 v20, 0x80, v7
	v_cvt_pk_bf16_f32 v21, v72, v73
	v_cvt_pk_bf16_f32 v22, v74, v75
	ds_write_b16 v20, v21
	ds_write_b16_d16_hi v20, v21 offset:512
	ds_write_b16 v20, v22 offset:1024
	ds_write_b16_d16_hi v20, v22 offset:1536
	v_xor_b32_e32 v20, 0xc0, v7
	v_cvt_pk_bf16_f32 v21, v76, v77
	v_cvt_pk_bf16_f32 v22, v78, v79
	ds_write_b16 v20, v21
	ds_write_b16_d16_hi v20, v21 offset:512
	ds_write_b16 v20, v22 offset:1024
	ds_write_b16_d16_hi v20, v22 offset:1536
	v_xor_b32_e32 v20, 0x100, v7
	v_cvt_pk_bf16_f32 v21, v80, v81
	v_cvt_pk_bf16_f32 v22, v82, v83
	ds_write_b16 v20, v21
	ds_write_b16_d16_hi v20, v21 offset:512
	ds_write_b16 v20, v22 offset:1024
	ds_write_b16_d16_hi v20, v22 offset:1536
	v_xor_b32_e32 v20, 0x140, v7
	v_cvt_pk_bf16_f32 v21, v84, v85
	v_cvt_pk_bf16_f32 v22, v86, v87
	ds_write_b16 v20, v21
	ds_write_b16_d16_hi v20, v21 offset:512
	ds_write_b16 v20, v22 offset:1024
	ds_write_b16_d16_hi v20, v22 offset:1536
	v_xor_b32_e32 v20, 0x180, v7
	v_cvt_pk_bf16_f32 v21, v88, v89
	v_cvt_pk_bf16_f32 v22, v90, v91
	ds_write_b16 v20, v21
	ds_write_b16_d16_hi v20, v21 offset:512
	ds_write_b16 v20, v22 offset:1024
	ds_write_b16_d16_hi v20, v22 offset:1536
	v_xor_b32_e32 v20, 0x1c0, v7
	v_cvt_pk_bf16_f32 v21, v92, v93
	v_cvt_pk_bf16_f32 v22, v94, v95
	ds_write_b16 v20, v21
	ds_write_b16_d16_hi v20, v21 offset:512
	ds_write_b16 v20, v22 offset:1024
	ds_write_b16_d16_hi v20, v22 offset:1536
	s_waitcnt lgkmcnt(0)
	s_barrier
	ds_read_b128 v[48:51], v8
	ds_read_b128 v[52:55], v9
	ds_read_b128 v[56:59], v10
	ds_read_b128 v[60:63], v11
	v_mul_lo_u32 v13, v16, s47
	v_add_u32_e32 v13, v13, v17
	s_mov_b32 s4, s44
	s_mov_b32 s5, s45
	s_waitcnt lgkmcnt(3)
	global_store_dwordx4 v13, v[48:51], s[4:5]
	s_add_u32 s4, s4, s46
	s_addc_u32 s5, s5, 0
	s_waitcnt lgkmcnt(2)
	global_store_dwordx4 v13, v[52:55], s[4:5]
	s_add_u32 s4, s4, s46
	s_addc_u32 s5, s5, 0
	s_waitcnt lgkmcnt(1)
	global_store_dwordx4 v13, v[56:59], s[4:5]
	s_add_u32 s4, s4, s46
	s_addc_u32 s5, s5, 0
	s_waitcnt lgkmcnt(0)
	global_store_dwordx4 v13, v[60:63], s[4:5]
	s_branch .Ltr_loop_B
.Ltr_onlyA:
	s_waitcnt vmcnt(0)
	s_barrier
	v_xor_b32_e32 v20, 0x0, v7
	v_cvt_pk_bf16_f32 v21, v64, v65
	v_cvt_pk_bf16_f32 v22, v66, v67
	ds_write_b16 v20, v21
	ds_write_b16_d16_hi v20, v21 offset:512
	ds_write_b16 v20, v22 offset:1024
	ds_write_b16_d16_hi v20, v22 offset:1536
	v_xor_b32_e32 v20, 0x40, v7
	v_cvt_pk_bf16_f32 v21, v68, v69
	v_cvt_pk_bf16_f32 v22, v70, v71
	ds_write_b16 v20, v21
	ds_write_b16_d16_hi v20, v21 offset:512
	ds_write_b16 v20, v22 offset:1024
	ds_write_b16_d16_hi v20, v22 offset:1536
	v_xor_b32_e32 v20, 0x80, v7
	v_cvt_pk_bf16_f32 v21, v72, v73
	v_cvt_pk_bf16_f32 v22, v74, v75
	ds_write_b16 v20, v21
	ds_write_b16_d16_hi v20, v21 offset:512
	ds_write_b16 v20, v22 offset:1024
	ds_write_b16_d16_hi v20, v22 offset:1536
	v_xor_b32_e32 v20, 0xc0, v7
	v_cvt_pk_bf16_f32 v21, v76, v77
	v_cvt_pk_bf16_f32 v22, v78, v79
	ds_write_b16 v20, v21
	ds_write_b16_d16_hi v20, v21 offset:512
	ds_write_b16 v20, v22 offset:1024
	ds_write_b16_d16_hi v20, v22 offset:1536
	v_xor_b32_e32 v20, 0x100, v7
	v_cvt_pk_bf16_f32 v21, v80, v81
	v_cvt_pk_bf16_f32 v22, v82, v83
	ds_write_b16 v20, v21
	ds_write_b16_d16_hi v20, v21 offset:512
	ds_write_b16 v20, v22 offset:1024
	ds_write_b16_d16_hi v20, v22 offset:1536
	v_xor_b32_e32 v20, 0x140, v7
	v_cvt_pk_bf16_f32 v21, v84, v85
	v_cvt_pk_bf16_f32 v22, v86, v87
	ds_write_b16 v20, v21
	ds_write_b16_d16_hi v20, v21 offset:512
	ds_write_b16 v20, v22 offset:1024
	ds_write_b16_d16_hi v20, v22 offset:1536
	v_xor_b32_e32 v20, 0x180, v7
	v_cvt_pk_bf16_f32 v21, v88, v89
	v_cvt_pk_bf16_f32 v22, v90, v91
	ds_write_b16 v20, v21
	ds_write_b16_d16_hi v20, v21 offset:512
	ds_write_b16 v20, v22 offset:1024
	ds_write_b16_d16_hi v20, v22 offset:1536
	v_xor_b32_e32 v20, 0x1c0, v7
	v_cvt_pk_bf16_f32 v21, v92, v93
	v_cvt_pk_bf16_f32 v22, v94, v95
	ds_write_b16 v20, v21
	ds_write_b16_d16_hi v20, v21 offset:512
	ds_write_b16 v20, v22 offset:1024
	ds_write_b16_d16_hi v20, v22 offset:1536
	s_waitcnt lgkmcnt(0)
	s_barrier
	ds_read_b128 v[48:51], v8
	ds_read_b128 v[52:55], v9
	ds_read_b128 v[56:59], v10
	ds_read_b128 v[60:63], v11
	v_mul_lo_u32 v13, v16, s47
	v_add_u32_e32 v13, v13, v17
	s_mov_b32 s4, s44
	s_mov_b32 s5, s45
	s_waitcnt lgkmcnt(3)
	global_store_dwordx4 v13, v[48:51], s[4:5]
	s_add_u32 s4, s4, s46
	s_addc_u32 s5, s5, 0
	s_waitcnt lgkmcnt(2)
	global_store_dwordx4 v13, v[52:55], s[4:5]
	s_add_u32 s4, s4, s46
	s_addc_u32 s5, s5, 0
	s_waitcnt lgkmcnt(1)
	global_store_dwordx4 v13, v[56:59], s[4:5]
	s_add_u32 s4, s4, s46
	s_addc_u32 s5, s5, 0
	s_waitcnt lgkmcnt(0)
	global_store_dwordx4 v13, v[60:63], s[4:5]
	s_branch .Ltr_done
.Ltr_loop:
	s_add_i32 s22, s22, s24
	s_cmpk_gt_i32 s22, 0x26a8
	s_cbranch_scc1 .Ltr_lastA
	s_add_i32 s0, s22, 0xfffffbe7
	s_mov_b32 s1, 0
	s_cmpk_ge_u32 s0, 0x8a4
	s_cbranch_scc0 .Ltr_l2
	s_addk_i32 s0, 0xf75c
	s_add_i32 s1, s1, 1
	s_cmpk_ge_u32 s0, 0x8a4
	s_cbranch_scc0 .Ltr_l2
	s_addk_i32 s0, 0xf75c
	s_add_i32 s1, s1, 1
	s_cmpk_ge_u32 s0, 0x8a4
	s_cbranch_scc0 .Ltr_l2
	s_addk_i32 s0, 0xf75c
	s_add_i32 s1, s1, 1

.Ltr_dd2:
	v_readlane_b32 s6, v247, 39
	v_readlane_b32 s7, v247, 40
	s_add_u32 s52, s6, s3
	s_addc_u32 s53, s7, 0
	v_mul_lo_u32 v12, v14, s51
	v_add_u32_e32 v12, v12, v15
	s_mov_b32 s4, s48
	s_mov_b32 s5, s49
	global_load_dwordx4 v[96:99], v12, s[4:5] nt
	s_add_u32 s4, s4, s50
	s_addc_u32 s5, s5, 0
	global_load_dwordx4 v[100:103], v12, s[4:5] nt
	s_add_u32 s4, s4, s50
	s_addc_u32 s5, s5, 0
	global_load_dwordx4 v[104:107], v12, s[4:5] nt
	s_add_u32 s4, s4, s50
	s_addc_u32 s5, s5, 0
	global_load_dwordx4 v[108:111], v12, s[4:5] nt
	s_add_u32 s4, s4, s50
	s_addc_u32 s5, s5, 0
	global_load_dwordx4 v[112:115], v12, s[4:5] nt
	s_add_u32 s4, s4, s50
	s_addc_u32 s5, s5, 0
	global_load_dwordx4 v[116:119], v12, s[4:5] nt
	s_add_u32 s4, s4, s50
	s_addc_u32 s5, s5, 0
	global_load_dwordx4 v[120:123], v12, s[4:5] nt
	s_add_u32 s4, s4, s50
	s_addc_u32 s5, s5, 0
	global_load_dwordx4 v[124:127], v12, s[4:5] nt
	s_waitcnt vmcnt(12)
	s_barrier
	v_xor_b32_e32 v20, 0x0, v7
	v_cvt_pk_bf16_f32 v21, v64, v65
	v_cvt_pk_bf16_f32 v22, v66, v67
	ds_write_b16 v20, v21
	ds_write_b16_d16_hi v20, v21 offset:512
	ds_write_b16 v20, v22 offset:1024
	ds_write_b16_d16_hi v20, v22 offset:1536
	v_xor_b32_e32 v20, 0x40, v7
	v_cvt_pk_bf16_f32 v21, v68, v69
	v_cvt_pk_bf16_f32 v22, v70, v71
	ds_write_b16 v20, v21
	ds_write_b16_d16_hi v20, v21 offset:512
	ds_write_b16 v20, v22 offset:1024
	ds_write_b16_d16_hi v20, v22 offset:1536
	v_xor_b32_e32 v20, 0x80, v7
	v_cvt_pk_bf16_f32 v21, v72, v73
	v_cvt_pk_bf16_f32 v22, v74, v75
	ds_write_b16 v20, v21
	ds_write_b16_d16_hi v20, v21 offset:512
	ds_write_b16 v20, v22 offset:1024
	ds_write_b16_d16_hi v20, v22 offset:1536
	v_xor_b32_e32 v20, 0xc0, v7
	v_cvt_pk_bf16_f32 v21, v76, v77
	v_cvt_pk_bf16_f32 v22, v78, v79
	ds_write_b16 v20, v21
	ds_write_b16_d16_hi v20, v21 offset:512
	ds_write_b16 v20, v22 offset:1024
	ds_write_b16_d16_hi v20, v22 offset:1536
	v_xor_b32_e32 v20, 0x100, v7
	v_cvt_pk_bf16_f32 v21, v80, v81
	v_cvt_pk_bf16_f32 v22, v82, v83
	ds_write_b16 v20, v21
	ds_write_b16_d16_hi v20, v21 offset:512
	ds_write_b16 v20, v22 offset:1024
	ds_write_b16_d16_hi v20, v22 offset:1536
	v_xor_b32_e32 v20, 0x140, v7
	v_cvt_pk_bf16_f32 v21, v84, v85
	v_cvt_pk_bf16_f32 v22, v86, v87
	ds_write_b16 v20, v21
	ds_write_b16_d16_hi v20, v21 offset:512
	ds_write_b16 v20, v22 offset:1024
	ds_write_b16_d16_hi v20, v22 offset:1536
	v_xor_b32_e32 v20, 0x180, v7
	v_cvt_pk_bf16_f32 v21, v88, v89
	v_cvt_pk_bf16_f32 v22, v90, v91
	ds_write_b16 v20, v21
	ds_write_b16_d16_hi v20, v21 offset:512
	ds_write_b16 v20, v22 offset:1024
	ds_write_b16_d16_hi v20, v22 offset:1536
	v_xor_b32_e32 v20, 0x1c0, v7
	v_cvt_pk_bf16_f32 v21, v92, v93
	v_cvt_pk_bf16_f32 v22, v94, v95
	ds_write_b16 v20, v21
	ds_write_b16_d16_hi v20, v21 offset:512
	ds_write_b16 v20, v22 offset:1024
	ds_write_b16_d16_hi v20, v22 offset:1536
	s_waitcnt lgkmcnt(0)
	s_barrier
	ds_read_b128 v[48:51], v8
	ds_read_b128 v[52:55], v9
	ds_read_b128 v[56:59], v10
	ds_read_b128 v[60:63], v11
	v_mul_lo_u32 v13, v16, s47
	v_add_u32_e32 v13, v13, v17
	s_mov_b32 s4, s44
	s_mov_b32 s5, s45
	s_waitcnt lgkmcnt(3)
	global_store_dwordx4 v13, v[48:51], s[4:5]
	s_add_u32 s4, s4, s46
	s_addc_u32 s5, s5, 0
	s_waitcnt lgkmcnt(2)
	global_store_dwordx4 v13, v[52:55], s[4:5]
	s_add_u32 s4, s4, s46
	s_addc_u32 s5, s5, 0
	s_waitcnt lgkmcnt(1)
	global_store_dwordx4 v13, v[56:59], s[4:5]
	s_add_u32 s4, s4, s46
	s_addc_u32 s5, s5, 0
	s_waitcnt lgkmcnt(0)
	global_store_dwordx4 v13, v[60:63], s[4:5]

.Ltr_dd3:
	v_readlane_b32 s6, v247, 39
	v_readlane_b32 s7, v247, 40
	s_add_u32 s44, s6, s3
	s_addc_u32 s45, s7, 0
	v_mul_lo_u32 v12, v14, s43
	v_add_u32_e32 v12, v12, v15
	s_mov_b32 s4, s40
	s_mov_b32 s5, s41
	global_load_dwordx4 v[64:67], v12, s[4:5] nt
	s_add_u32 s4, s4, s42
	s_addc_u32 s5, s5, 0
	global_load_dwordx4 v[68:71], v12, s[4:5] nt
	s_add_u32 s4, s4, s42
	s_addc_u32 s5, s5, 0
	global_load_dwordx4 v[72:75], v12, s[4:5] nt
	s_add_u32 s4, s4, s42
	s_addc_u32 s5, s5, 0
	global_load_dwordx4 v[76:79], v12, s[4:5] nt
	s_add_u32 s4, s4, s42
	s_addc_u32 s5, s5, 0
	global_load_dwordx4 v[80:83], v12, s[4:5] nt
	s_add_u32 s4, s4, s42
	s_addc_u32 s5, s5, 0
	global_load_dwordx4 v[84:87], v12, s[4:5] nt
	s_add_u32 s4, s4, s42
	s_addc_u32 s5, s5, 0
	global_load_dwordx4 v[88:91], v12, s[4:5] nt
	s_add_u32 s4, s4, s42
	s_addc_u32 s5, s5, 0
	global_load_dwordx4 v[92:95], v12, s[4:5] nt
	s_waitcnt vmcnt(12)
	s_barrier
	v_xor_b32_e32 v20, 0x0, v7
	v_cvt_pk_bf16_f32 v21, v96, v97
	v_cvt_pk_bf16_f32 v22, v98, v99
	ds_write_b16 v20, v21
	ds_write_b16_d16_hi v20, v21 offset:512
	ds_write_b16 v20, v22 offset:1024
	ds_write_b16_d16_hi v20, v22 offset:1536
	v_xor_b32_e32 v20, 0x40, v7
	v_cvt_pk_bf16_f32 v21, v100, v101
	v_cvt_pk_bf16_f32 v22, v102, v103
	ds_write_b16 v20, v21
	ds_write_b16_d16_hi v20, v21 offset:512
	ds_write_b16 v20, v22 offset:1024
	ds_write_b16_d16_hi v20, v22 offset:1536
	v_xor_b32_e32 v20, 0x80, v7
	v_cvt_pk_bf16_f32 v21, v104, v105
	v_cvt_pk_bf16_f32 v22, v106, v107
	ds_write_b16 v20, v21
	ds_write_b16_d16_hi v20, v21 offset:512
	ds_write_b16 v20, v22 offset:1024
	ds_write_b16_d16_hi v20, v22 offset:1536
	v_xor_b32_e32 v20, 0xc0, v7
	v_cvt_pk_bf16_f32 v21, v108, v109
	v_cvt_pk_bf16_f32 v22, v110, v111
	ds_write_b16 v20, v21
	ds_write_b16_d16_hi v20, v21 offset:512
	ds_write_b16 v20, v22 offset:1024
	ds_write_b16_d16_hi v20, v22 offset:1536
	v_xor_b32_e32 v20, 0x100, v7
	v_cvt_pk_bf16_f32 v21, v112, v113
	v_cvt_pk_bf16_f32 v22, v114, v115
	ds_write_b16 v20, v21
	ds_write_b16_d16_hi v20, v21 offset:512
	ds_write_b16 v20, v22 offset:1024
	ds_write_b16_d16_hi v20, v22 offset:1536
	v_xor_b32_e32 v20, 0x140, v7
	v_cvt_pk_bf16_f32 v21, v116, v117
	v_cvt_pk_bf16_f32 v22, v118, v119
	ds_write_b16 v20, v21
	ds_write_b16_d16_hi v20, v21 offset:512
	ds_write_b16 v20, v22 offset:1024
	ds_write_b16_d16_hi v20, v22 offset:1536
	v_xor_b32_e32 v20, 0x180, v7
	v_cvt_pk_bf16_f32 v21, v120, v121
	v_cvt_pk_bf16_f32 v22, v122, v123
	ds_write_b16 v20, v21
	ds_write_b16_d16_hi v20, v21 offset:512
	ds_write_b16 v20, v22 offset:1024
	ds_write_b16_d16_hi v20, v22 offset:1536
	v_xor_b32_e32 v20, 0x1c0, v7
	v_cvt_pk_bf16_f32 v21, v124, v125
	v_cvt_pk_bf16_f32 v22, v126, v127
	ds_write_b16 v20, v21
	ds_write_b16_d16_hi v20, v21 offset:512
	ds_write_b16 v20, v22 offset:1024
	ds_write_b16_d16_hi v20, v22 offset:1536
	s_waitcnt lgkmcnt(0)
	s_barrier
	ds_read_b128 v[48:51], v8
	ds_read_b128 v[52:55], v9
	ds_read_b128 v[56:59], v10
	ds_read_b128 v[60:63], v11
	v_mul_lo_u32 v13, v16, s55
	v_add_u32_e32 v13, v13, v17
	s_mov_b32 s4, s52
	s_mov_b32 s5, s53
	s_waitcnt lgkmcnt(3)
	global_store_dwordx4 v13, v[48:51], s[4:5]
	s_add_u32 s4, s4, s54
	s_addc_u32 s5, s5, 0
	s_waitcnt lgkmcnt(2)
	global_store_dwordx4 v13, v[52:55], s[4:5]
	s_add_u32 s4, s4, s54
	s_addc_u32 s5, s5, 0
	s_waitcnt lgkmcnt(1)
	global_store_dwordx4 v13, v[56:59], s[4:5]
	s_add_u32 s4, s4, s54
	s_addc_u32 s5, s5, 0
	s_waitcnt lgkmcnt(0)
	global_store_dwordx4 v13, v[60:63], s[4:5]
	s_branch .Ltr_loop
.Ltr_lastA:
	s_waitcnt vmcnt(4)
	s_barrier
	v_xor_b32_e32 v20, 0x0, v7
	v_cvt_pk_bf16_f32 v21, v64, v65
	v_cvt_pk_bf16_f32 v22, v66, v67
	ds_write_b16 v20, v21
	ds_write_b16_d16_hi v20, v21 offset:512
	ds_write_b16 v20, v22 offset:1024
	ds_write_b16_d16_hi v20, v22 offset:1536
	v_xor_b32_e32 v20, 0x40, v7
	v_cvt_pk_bf16_f32 v21, v68, v69
	v_cvt_pk_bf16_f32 v22, v70, v71
	ds_write_b16 v20, v21
	ds_write_b16_d16_hi v20, v21 offset:512
	ds_write_b16 v20, v22 offset:1024
	ds_write_b16_d16_hi v20, v22 offset:1536
	v_xor_b32_e32 v20, 0x80, v7
	v_cvt_pk_bf16_f32 v21, v72, v73
	v_cvt_pk_bf16_f32 v22, v74, v75
	ds_write_b16 v20, v21
	ds_write_b16_d16_hi v20, v21 offset:512
	ds_write_b16 v20, v22 offset:1024
	ds_write_b16_d16_hi v20, v22 offset:1536
	v_xor_b32_e32 v20, 0xc0, v7
	v_cvt_pk_bf16_f32 v21, v76, v77
	v_cvt_pk_bf16_f32 v22, v78, v79
	ds_write_b16 v20, v21
	ds_write_b16_d16_hi v20, v21 offset:512
	ds_write_b16 v20, v22 offset:1024
	ds_write_b16_d16_hi v20, v22 offset:1536
	v_xor_b32_e32 v20, 0x100, v7
	v_cvt_pk_bf16_f32 v21, v80, v81
	v_cvt_pk_bf16_f32 v22, v82, v83
	ds_write_b16 v20, v21
	ds_write_b16_d16_hi v20, v21 offset:512
	ds_write_b16 v20, v22 offset:1024
	ds_write_b16_d16_hi v20, v22 offset:1536
	v_xor_b32_e32 v20, 0x140, v7
	v_cvt_pk_bf16_f32 v21, v84, v85
	v_cvt_pk_bf16_f32 v22, v86, v87
	ds_write_b16 v20, v21
	ds_write_b16_d16_hi v20, v21 offset:512
	ds_write_b16 v20, v22 offset:1024
	ds_write_b16_d16_hi v20, v22 offset:1536
	v_xor_b32_e32 v20, 0x180, v7
	v_cvt_pk_bf16_f32 v21, v88, v89
	v_cvt_pk_bf16_f32 v22, v90, v91
	ds_write_b16 v20, v21
	ds_write_b16_d16_hi v20, v21 offset:512
	ds_write_b16 v20, v22 offset:1024
	ds_write_b16_d16_hi v20, v22 offset:1536
	v_xor_b32_e32 v20, 0x1c0, v7
	v_cvt_pk_bf16_f32 v21, v92, v93
	v_cvt_pk_bf16_f32 v22, v94, v95
	ds_write_b16 v20, v21
	ds_write_b16_d16_hi v20, v21 offset:512
	ds_write_b16 v20, v22 offset:1024
	ds_write_b16_d16_hi v20, v22 offset:1536
	s_waitcnt lgkmcnt(0)
	s_barrier
	ds_read_b128 v[48:51], v8
	ds_read_b128 v[52:55], v9
	ds_read_b128 v[56:59], v10
	ds_read_b128 v[60:63], v11
	v_mul_lo_u32 v13, v16, s47
	v_add_u32_e32 v13, v13, v17
	s_mov_b32 s4, s44
	s_mov_b32 s5, s45
	s_waitcnt lgkmcnt(3)
	global_store_dwordx4 v13, v[48:51], s[4:5]
	s_add_u32 s4, s4, s46
	s_addc_u32 s5, s5, 0
	s_waitcnt lgkmcnt(2)
	global_store_dwordx4 v13, v[52:55], s[4:5]
	s_add_u32 s4, s4, s46
	s_addc_u32 s5, s5, 0
	s_waitcnt lgkmcnt(1)
	global_store_dwordx4 v13, v[56:59], s[4:5]
	s_add_u32 s4, s4, s46
	s_addc_u32 s5, s5, 0
	s_waitcnt lgkmcnt(0)
	global_store_dwordx4 v13, v[60:63], s[4:5]
	s_branch .Ltr_done
.Ltr_lastB:
	s_waitcnt vmcnt(4)
	s_barrier
	v_xor_b32_e32 v20, 0x0, v7
	v_cvt_pk_bf16_f32 v21, v96, v97
	v_cvt_pk_bf16_f32 v22, v98, v99
	ds_write_b16 v20, v21
	ds_write_b16_d16_hi v20, v21 offset:512
	ds_write_b16 v20, v22 offset:1024
	ds_write_b16_d16_hi v20, v22 offset:1536
	v_xor_b32_e32 v20, 0x40, v7
	v_cvt_pk_bf16_f32 v21, v100, v101
	v_cvt_pk_bf16_f32 v22, v102, v103
	ds_write_b16 v20, v21
	ds_write_b16_d16_hi v20, v21 offset:512
	ds_write_b16 v20, v22 offset:1024
	ds_write_b16_d16_hi v20, v22 offset:1536
	v_xor_b32_e32 v20, 0x80, v7
	v_cvt_pk_bf16_f32 v21, v104, v105
	v_cvt_pk_bf16_f32 v22, v106, v107
	ds_write_b16 v20, v21
	ds_write_b16_d16_hi v20, v21 offset:512
	ds_write_b16 v20, v22 offset:1024
	ds_write_b16_d16_hi v20, v22 offset:1536
	v_xor_b32_e32 v20, 0xc0, v7
	v_cvt_pk_bf16_f32 v21, v108, v109
	v_cvt_pk_bf16_f32 v22, v110, v111
	ds_write_b16 v20, v21
	ds_write_b16_d16_hi v20, v21 offset:512
	ds_write_b16 v20, v22 offset:1024
	ds_write_b16_d16_hi v20, v22 offset:1536
	v_xor_b32_e32 v20, 0x100, v7
	v_cvt_pk_bf16_f32 v21, v112, v113
	v_cvt_pk_bf16_f32 v22, v114, v115
	ds_write_b16 v20, v21
	ds_write_b16_d16_hi v20, v21 offset:512
	ds_write_b16 v20, v22 offset:1024
	ds_write_b16_d16_hi v20, v22 offset:1536
	v_xor_b32_e32 v20, 0x140, v7
	v_cvt_pk_bf16_f32 v21, v116, v117
	v_cvt_pk_bf16_f32 v22, v118, v119
	ds_write_b16 v20, v21
	ds_write_b16_d16_hi v20, v21 offset:512
	ds_write_b16 v20, v22 offset:1024
	ds_write_b16_d16_hi v20, v22 offset:1536
	v_xor_b32_e32 v20, 0x180, v7
	v_cvt_pk_bf16_f32 v21, v120, v121
	v_cvt_pk_bf16_f32 v22, v122, v123
	ds_write_b16 v20, v21
	ds_write_b16_d16_hi v20, v21 offset:512
	ds_write_b16 v20, v22 offset:1024
	ds_write_b16_d16_hi v20, v22 offset:1536
	v_xor_b32_e32 v20, 0x1c0, v7
	v_cvt_pk_bf16_f32 v21, v124, v125
	v_cvt_pk_bf16_f32 v22, v126, v127
	ds_write_b16 v20, v21
	ds_write_b16_d16_hi v20, v21 offset:512
	ds_write_b16 v20, v22 offset:1024
	ds_write_b16_d16_hi v20, v22 offset:1536
	s_waitcnt lgkmcnt(0)
	s_barrier
	ds_read_b128 v[48:51], v8
	ds_read_b128 v[52:55], v9
	ds_read_b128 v[56:59], v10
	ds_read_b128 v[60:63], v11
	v_mul_lo_u32 v13, v16, s55
	v_add_u32_e32 v13, v13, v17
	s_mov_b32 s4, s52
	s_mov_b32 s5, s53
	s_waitcnt lgkmcnt(3)
	global_store_dwordx4 v13, v[48:51], s[4:5]
	s_add_u32 s4, s4, s54
	s_addc_u32 s5, s5, 0
	s_waitcnt lgkmcnt(2)
	global_store_dwordx4 v13, v[52:55], s[4:5]
	s_add_u32 s4, s4, s54
	s_addc_u32 s5, s5, 0
	s_waitcnt lgkmcnt(1)
	global_store_dwordx4 v13, v[56:59], s[4:5]
	s_add_u32 s4, s4, s54
	s_addc_u32 s5, s5, 0
	s_waitcnt lgkmcnt(0)
	global_store_dwordx4 v13, v[60:63], s[4:5]
.Ltr_done:
	s_branch .LBB0_651
.LBB0_651:
	v_readlane_b32 s18, v247, 39
	v_readlane_b32 s19, v247, 40

.LBB0_683:
	s_or_b64 exec, exec, s[0:1]
	s_waitcnt vmcnt(0) lgkmcnt(0)
	s_waitcnt vmcnt(0)

.LBB0_701:
	s_or_b64 exec, exec, s[0:1]
	v_readlane_b32 s0, v247, 27
	v_readlane_b32 s1, v247, 28
	s_waitcnt vmcnt(0)
	s_nop 0
	s_nop 2
	global_atomic_add v153, v185, s[0:1]
	s_waitcnt vmcnt(0)
	s_branch .LBB0_702
.Lbar_inv:
	v_readfirstlane_b32 s0, v167
	s_mov_b64 exec, s[2:3]
	s_cmp_eq_u32 s0, 64
	s_cbranch_scc0 .LBB0_702
	buffer_inv sc1
	s_waitcnt vmcnt(0)

	.amdhsa_kernel _Z9trunk_fwd6Params
		.amdhsa_group_segment_fixed_size 73760
		.amdhsa_private_segment_fixed_size 0
		.amdhsa_kernarg_size 536
		.amdhsa_user_sgpr_count 2
		.amdhsa_user_sgpr_dispatch_ptr 0
		.amdhsa_user_sgpr_queue_ptr 0
		.amdhsa_user_sgpr_kernarg_segment_ptr 1
		.amdhsa_user_sgpr_dispatch_id 0
		.amdhsa_user_sgpr_kernarg_preload_length 0
		.amdhsa_user_sgpr_kernarg_preload_offset 0
		.amdhsa_user_sgpr_private_segment_size 0
		.amdhsa_uses_dynamic_stack 0
		.amdhsa_enable_private_segment 0
		.amdhsa_system_sgpr_workgroup_id_x 1
		.amdhsa_system_sgpr_workgroup_id_y 0
		.amdhsa_system_sgpr_workgroup_id_z 0
		.amdhsa_system_sgpr_workgroup_info 0
		.amdhsa_system_vgpr_workitem_id 2
		.amdhsa_next_free_vgpr 250
		.amdhsa_next_free_sgpr 102
		.amdhsa_accum_offset 252
		.amdhsa_reserve_vcc 1
		.amdhsa_float_round_mode_32 0
		.amdhsa_float_round_mode_16_64 0
		.amdhsa_float_denorm_mode_32 3
		.amdhsa_float_denorm_mode_16_64 3
		.amdhsa_dx10_clamp 1
		.amdhsa_ieee_mode 1
		.amdhsa_fp16_overflow 0
		.amdhsa_tg_split 0
		.amdhsa_exception_fp_ieee_invalid_op 0
		.amdhsa_exception_fp_denorm_src 0
		.amdhsa_exception_fp_ieee_div_zero 0
		.amdhsa_exception_fp_ieee_overflow 0
		.amdhsa_exception_fp_ieee_underflow 0
		.amdhsa_exception_fp_ieee_inexact 0
		.amdhsa_exception_int_div_zero 0
	.end_amdhsa_kernel

amdhsa.kernels:
  - .agpr_count:     0
    .args:
      - .offset:         0
        .size:           280
        .value_kind:     by_value
      - .offset:         280
        .size:           4
        .value_kind:     hidden_block_count_x
      - .offset:         284
        .size:           4
        .value_kind:     hidden_block_count_y
      - .offset:         288
        .size:           4
        .value_kind:     hidden_block_count_z
      - .offset:         292
        .size:           2
        .value_kind:     hidden_group_size_x
      - .offset:         294
        .size:           2
        .value_kind:     hidden_group_size_y
      - .offset:         296
        .size:           2
        .value_kind:     hidden_group_size_z
      - .offset:         298
        .size:           2
        .value_kind:     hidden_remainder_x
      - .offset:         300
        .size:           2
        .value_kind:     hidden_remainder_y
      - .offset:         302
        .size:           2
        .value_kind:     hidden_remainder_z
      - .offset:         320
        .size:           8
        .value_kind:     hidden_global_offset_x
      - .offset:         328
        .size:           8
        .value_kind:     hidden_global_offset_y
      - .offset:         336
        .size:           8
        .value_kind:     hidden_global_offset_z
      - .offset:         344
        .size:           2
        .value_kind:     hidden_grid_dims
      - .offset:         368
        .size:           8
        .value_kind:     hidden_multigrid_sync_arg
    .group_segment_fixed_size: 73760
    .kernarg_segment_align: 8
    .kernarg_segment_size: 536
    .language:       OpenCL C
    .language_version:
      - 2
      - 0
    .max_flat_workgroup_size: 256
    .name:           _Z9trunk_fwd6Params
    .private_segment_fixed_size: 0
    .sgpr_count:     108
    .sgpr_spill_count: 195
    .symbol:         _Z9trunk_fwd6Params.kd
    .uniform_work_group_size: 1
    .uses_dynamic_stack: false
    .vgpr_count:     250
    .vgpr_spill_count: 0
    .wavefront_size: 64
